# branch B sliding K/V window: each workgroup walks 16 consecutive row pairs of one (b,h); per unit only 2 new grid rows are prefetched/committed into a 9-slot LDS ring (ring-slot addressing in the unit
# speedup vs baseline: 1.0439x; 1.0080x over previous
; __device__ __forceinline__ size_t tmo(int row, int ct, int nct) { return ((size_t)(row >> 8) * nct + ct) * 32768 + (size_t)(row & 255) * 128; }
; __device__ __forceinline__ void attn_b_prefetch(const bf16* Z, const float* rpb, int unit, v4u (&kr)[9], v4u (&vr)[9], float (&tr)[2]) {
;     const int tid = threadIdx.x; const int rp = unit & 63, h = (unit >> 6) & 7, b = unit >> 9;
;     const size_t tok0 = (size_t)b * SEQ; const int R0 = clampi(2 * rp - 4, 0, 120);
; #pragma unroll
;     for (int k = 0; k < 9; ++k) { const int it = tid + k * NTHREADS; const int row = it >> 3, ch = it & 7, gr = R0 + (row >> 6);
;         kr[k] = (v4u){0u, 0u, 0u, 0u}; vr[k] = (v4u){0u, 0u, 0u, 0u};
;         if (gr < 128) { const int t = (int)tok0 + gr * 64 + (row & 63); kr[k] = *(const v4u*)((const unsigned char*)Z + tmo(t, Z_KB / 64 + h, ZLD / 64) + ch * 16); vr[k] = *(const v4u*)((const unsigned char*)Z + tmo(t, Z_VB / 64 + h, ZLD / 64) + ch * 16); } }
; #pragma unroll
;     for (int k = 0; k < 2; ++k) { const int it = tid + k * NTHREADS, e = it - 16, dr = e >> 5, dc = e & 31;
;         tr[k] = (it >= B_TREAL) ? -INFINITY : ((e >= 0 && dr < 15 && dc < 31) ? rpb[h * 465 + dr * 31 + dc] * LOG2E : 0.f); }
; __global__ void __launch_bounds__(NTHREADS, 2) mk_fwd(Args args) {
;     ...
;         {
;             v4u kr[9], vr[9]; float tr[2]; int u = vcu; const int NU = BATCH * 8 * 64;
;             if (u < NU) attn_b_prefetch(Zb, rpb, u, kr, vr, tr);
;             for (; u < NU; u += G) {
;                 attn_b_commit(lds, kr, vr, tr);
;                 __syncthreads();
;                 if (u + G < NU) attn_b_prefetch(Zb, rpb, u + G, kr, vr, tr);
.LBB0_268:
	s_cmpk_gt_i32 s96, 0xfff
	s_cbranch_scc1 .LBB0_294
	s_mov_b32 s89, s96
	s_mov_b32 s90, s33
	s_mov_b32 s91, 0
	s_cmpk_lg_i32 s33, 0x100
	s_cbranch_scc1 .Lb_noslide
	s_lshr_b32 s89, s96, 2
	s_lshl_b32 s89, s89, 6
	s_and_b32 s90, s96, 3
	s_lshl_b32 s90, s90, 4
	s_or_b32 s89, s89, s90
	s_mov_b32 s90, 1
	s_mov_b32 s91, 1
.Lb_noslide:
	s_lshl_b32 s58, s89, 1
	s_and_b32 s3, s58, 0x7e
	s_waitcnt vmcnt(0)
	v_sub_co_u32_e64 v2, s[6:7], s3, 4
	s_lshl_b32 s59, s89, 4
	v_readfirstlane_b32 s3, v2
	s_bfe_u32 s0, s89, 0x30006
	s_and_b32 s1, s59, 0xffffe000
	s_min_u32 s3, s3, 0x78
	s_and_b64 s[6:7], s[6:7], exec
	s_cselect_b32 s3, 0, s3
	v_lshrrev_b32_e32 v106, 9, v218
	v_or_b32_e32 v59, s3, v106
	v_lshlrev_b32_e32 v58, 6, v59
	v_lshlrev_b32_e32 v2, 4, v218
	v_add_u32_e32 v10, 64, v58
	v_add_u32_e32 v18, 0x80, v58
	v_add_u32_e32 v26, 0xc0, v58
	v_add_u32_e32 v34, 0x100, v58
	v_add_u32_e32 v42, 0x140, v58
	v_add_u32_e32 v50, 0x180, v58
	v_bfe_u32 v107, v218, 3, 6
	v_and_b32_e32 v102, 0x70, v2
	v_or_b32_e32 v2, s1, v58
	v_or_b32_e32 v11, s1, v10
	v_or_b32_e32 v19, s1, v18
	v_or_b32_e32 v27, s1, v26
	v_or_b32_e32 v35, s1, v34
	v_or_b32_e32 v43, s1, v42
	v_or_b32_e32 v51, s1, v50
	v_lshrrev_b32_e32 v2, 8, v2
	v_or_b32_e32 v14, v10, v107
	v_lshrrev_b32_e32 v10, 8, v11
	v_or_b32_e32 v22, v18, v107
	v_lshrrev_b32_e32 v18, 8, v19
	v_or_b32_e32 v30, v26, v107
	v_lshrrev_b32_e32 v26, 8, v27
	v_or_b32_e32 v38, v34, v107
	v_lshrrev_b32_e32 v34, 8, v35
	v_or_b32_e32 v46, v42, v107
	v_lshrrev_b32_e32 v42, 8, v43
	v_or_b32_e32 v54, v50, v107
	v_lshrrev_b32_e32 v50, 8, v51
	s_mov_b32 s5, 0
	v_mul_i32_i24_e32 v2, 0x44, v2
	v_mul_i32_i24_e32 v10, 0x44, v10
	v_mul_i32_i24_e32 v18, 0x44, v18
	v_mul_i32_i24_e32 v26, 0x44, v26
	v_mul_i32_i24_e32 v34, 0x44, v34
	v_mul_i32_i24_e32 v42, 0x44, v42
	v_mul_i32_i24_e32 v50, 0x44, v50
	s_add_i32 s4, s0, 20
	s_add_i32 s6, s0, 28
	s_mov_b32 s7, s5
	v_ashrrev_i32_e32 v3, 31, v2
	v_ashrrev_i32_e32 v11, 31, v10
	v_ashrrev_i32_e32 v19, 31, v18
	v_ashrrev_i32_e32 v27, 31, v26
	v_ashrrev_i32_e32 v35, 31, v34
	v_ashrrev_i32_e32 v43, 31, v42
	v_ashrrev_i32_e32 v51, 31, v50
	v_or_b32_e32 v6, v58, v107
	v_lshl_add_u64 v[4:5], v[2:3], 0, s[4:5]
	v_lshl_add_u64 v[2:3], v[2:3], 0, s[6:7]
	v_lshl_add_u64 v[12:13], v[10:11], 0, s[4:5]
	v_lshl_add_u64 v[10:11], v[10:11], 0, s[6:7]
	v_lshl_add_u64 v[20:21], v[18:19], 0, s[4:5]
	v_lshl_add_u64 v[18:19], v[18:19], 0, s[6:7]
	v_lshl_add_u64 v[28:29], v[26:27], 0, s[4:5]
	v_lshl_add_u64 v[26:27], v[26:27], 0, s[6:7]
	v_lshl_add_u64 v[36:37], v[34:35], 0, s[4:5]
	v_lshl_add_u64 v[34:35], v[34:35], 0, s[6:7]
	v_lshl_add_u64 v[44:45], v[42:43], 0, s[4:5]
	v_lshl_add_u64 v[42:43], v[42:43], 0, s[6:7]
	v_lshl_add_u64 v[52:53], v[50:51], 0, s[4:5]
	v_lshl_add_u64 v[50:51], v[50:51], 0, s[6:7]
	v_mov_b32_e32 v103, 0
	v_lshlrev_b64 v[4:5], 15, v[4:5]
	v_lshlrev_b32_e32 v6, 7, v6
	v_lshlrev_b64 v[2:3], 15, v[2:3]
	v_lshlrev_b64 v[12:13], 15, v[12:13]
	v_lshlrev_b32_e32 v14, 7, v14
	v_lshlrev_b64 v[10:11], 15, v[10:11]
	v_lshlrev_b64 v[20:21], 15, v[20:21]
	v_lshlrev_b32_e32 v22, 7, v22
	v_lshlrev_b64 v[18:19], 15, v[18:19]
	v_lshlrev_b64 v[28:29], 15, v[28:29]
	v_lshlrev_b32_e32 v30, 7, v30
	v_lshlrev_b64 v[26:27], 15, v[26:27]
	v_lshlrev_b64 v[36:37], 15, v[36:37]
	v_lshlrev_b32_e32 v38, 7, v38
	v_lshlrev_b64 v[34:35], 15, v[34:35]
	v_lshlrev_b64 v[44:45], 15, v[44:45]
	v_lshlrev_b32_e32 v46, 7, v46
	v_lshlrev_b64 v[42:43], 15, v[42:43]
	v_lshlrev_b64 v[52:53], 15, v[52:53]
	v_lshlrev_b32_e32 v54, 7, v54
	v_lshlrev_b64 v[50:51], 15, v[50:51]
	v_and_b32_e32 v6, 0x7f80, v6
	v_mov_b32_e32 v7, v103
	v_lshl_add_u64 v[4:5], s[38:39], 0, v[4:5]
	v_lshl_add_u64 v[2:3], s[38:39], 0, v[2:3]
	v_and_b32_e32 v14, 0x7f80, v14
	v_mov_b32_e32 v15, v103
	v_lshl_add_u64 v[12:13], s[38:39], 0, v[12:13]
	v_lshl_add_u64 v[10:11], s[38:39], 0, v[10:11]
	v_and_b32_e32 v22, 0x7f80, v22
	v_mov_b32_e32 v23, v103
	v_lshl_add_u64 v[20:21], s[38:39], 0, v[20:21]
	v_lshl_add_u64 v[18:19], s[38:39], 0, v[18:19]
	v_and_b32_e32 v30, 0x7f80, v30
	v_mov_b32_e32 v31, v103
	v_lshl_add_u64 v[28:29], s[38:39], 0, v[28:29]
	v_lshl_add_u64 v[26:27], s[38:39], 0, v[26:27]
	v_and_b32_e32 v38, 0x7f80, v38
	v_mov_b32_e32 v39, v103
	v_lshl_add_u64 v[36:37], s[38:39], 0, v[36:37]
	v_lshl_add_u64 v[34:35], s[38:39], 0, v[34:35]
	v_and_b32_e32 v46, 0x7f80, v46
	v_mov_b32_e32 v47, v103
	v_lshl_add_u64 v[44:45], s[38:39], 0, v[44:45]
	v_lshl_add_u64 v[42:43], s[38:39], 0, v[42:43]
	v_and_b32_e32 v54, 0x7f80, v54
	v_mov_b32_e32 v55, v103
	v_lshl_add_u64 v[52:53], s[38:39], 0, v[52:53]
	v_lshl_add_u64 v[50:51], s[38:39], 0, v[50:51]
	v_lshl_add_u64 v[4:5], v[4:5], 0, v[6:7]
	v_lshl_add_u64 v[2:3], v[2:3], 0, v[6:7]
	v_lshl_add_u64 v[12:13], v[12:13], 0, v[14:15]
	v_lshl_add_u64 v[10:11], v[10:11], 0, v[14:15]
	v_lshl_add_u64 v[20:21], v[20:21], 0, v[22:23]
	v_lshl_add_u64 v[18:19], v[18:19], 0, v[22:23]
	v_lshl_add_u64 v[28:29], v[28:29], 0, v[30:31]
	v_lshl_add_u64 v[26:27], v[26:27], 0, v[30:31]
	v_lshl_add_u64 v[36:37], v[36:37], 0, v[38:39]
	v_lshl_add_u64 v[34:35], v[34:35], 0, v[38:39]
	v_lshl_add_u64 v[44:45], v[44:45], 0, v[46:47]
	v_lshl_add_u64 v[42:43], v[42:43], 0, v[46:47]
	v_lshl_add_u64 v[52:53], v[52:53], 0, v[54:55]
	v_lshl_add_u64 v[50:51], v[50:51], 0, v[54:55]
	v_lshl_add_u64 v[4:5], v[4:5], 0, v[102:103]
	v_lshl_add_u64 v[6:7], v[2:3], 0, v[102:103]
	v_lshl_add_u64 v[12:13], v[12:13], 0, v[102:103]
	v_lshl_add_u64 v[14:15], v[10:11], 0, v[102:103]
	v_lshl_add_u64 v[20:21], v[20:21], 0, v[102:103]
	v_lshl_add_u64 v[22:23], v[18:19], 0, v[102:103]
	v_lshl_add_u64 v[28:29], v[28:29], 0, v[102:103]
	v_lshl_add_u64 v[30:31], v[26:27], 0, v[102:103]
	v_lshl_add_u64 v[36:37], v[36:37], 0, v[102:103]
	v_lshl_add_u64 v[38:39], v[34:35], 0, v[102:103]
	v_lshl_add_u64 v[44:45], v[44:45], 0, v[102:103]
	v_lshl_add_u64 v[46:47], v[42:43], 0, v[102:103]
	v_lshl_add_u64 v[52:53], v[52:53], 0, v[102:103]
	v_lshl_add_u64 v[54:55], v[50:51], 0, v[102:103]
	global_load_dwordx4 v[2:5], v[4:5], off
	s_nop 0
	global_load_dwordx4 v[6:9], v[6:7], off
	s_nop 0
	global_load_dwordx4 v[10:13], v[12:13], off
	s_nop 0
	global_load_dwordx4 v[14:17], v[14:15], off
	s_nop 0
	global_load_dwordx4 v[18:21], v[20:21], off
	s_nop 0
	global_load_dwordx4 v[22:25], v[22:23], off
	s_nop 0
	global_load_dwordx4 v[26:29], v[28:29], off
	s_nop 0
	global_load_dwordx4 v[30:33], v[30:31], off
	s_nop 0
	global_load_dwordx4 v[34:37], v[36:37], off
	s_nop 0
	global_load_dwordx4 v[38:41], v[38:39], off
	s_nop 0
	global_load_dwordx4 v[42:45], v[44:45], off
	s_nop 0
	global_load_dwordx4 v[46:49], v[46:47], off
	s_nop 0
	global_load_dwordx4 v[50:53], v[52:53], off
	s_nop 0
	global_load_dwordx4 v[54:57], v[54:55], off
	v_mov_b32_e32 v64, v103
	v_mov_b32_e32 v65, v103
	s_movk_i32 s8, 0x79
	v_mov_b32_e32 v62, v103
	v_mov_b32_e32 v63, v103
	v_mov_b64_e32 v[68:69], v[64:65]
	v_cmp_gt_u32_e32 vcc, s8, v59
	v_mov_b64_e32 v[66:67], v[62:63]
	s_and_saveexec_b64 s[8:9], vcc
	s_cbranch_execz .LBB0_271
; __device__ __forceinline__ size_t tmo(int row, int ct, int nct) { return ((size_t)(row >> 8) * nct + ct) * 32768 + (size_t)(row & 255) * 128; }
; __device__ __forceinline__ void attn_b_prefetch(const bf16* Z, const float* rpb, int unit, v4u (&kr)[9], v4u (&vr)[9], float (&tr)[2]) {
;     const int tid = threadIdx.x; const int rp = unit & 63, h = (unit >> 6) & 7, b = unit >> 9;
;     const size_t tok0 = (size_t)b * SEQ; const int R0 = clampi(2 * rp - 4, 0, 120);
; #pragma unroll
;     for (int k = 0; k < 9; ++k) { const int it = tid + k * NTHREADS; const int row = it >> 3, ch = it & 7, gr = R0 + (row >> 6);
;         kr[k] = (v4u){0u, 0u, 0u, 0u}; vr[k] = (v4u){0u, 0u, 0u, 0u};
;         if (gr < 128) { const int t = (int)tok0 + gr * 64 + (row & 63); kr[k] = *(const v4u*)((const unsigned char*)Z + tmo(t, Z_KB / 64 + h, ZLD / 64) + ch * 16); vr[k] = *(const v4u*)((const unsigned char*)Z + tmo(t, Z_VB / 64 + h, ZLD / 64) + ch * 16); } }
	v_add_u32_e32 v59, 0x1c0, v58
	v_or_b32_e32 v60, s1, v59
	v_lshrrev_b32_e32 v60, 8, v60
	v_mul_i32_i24_e32 v60, 0x44, v60
	v_ashrrev_i32_e32 v61, 31, v60
	v_or_b32_e32 v59, v59, v107
	v_lshl_add_u64 v[62:63], v[60:61], 0, s[4:5]
	v_lshlrev_b64 v[62:63], 15, v[62:63]
	v_lshlrev_b32_e32 v59, 7, v59
	v_lshl_add_u64 v[60:61], v[60:61], 0, s[6:7]
	v_and_b32_e32 v64, 0x7f80, v59
	v_mov_b32_e32 v65, v103
	v_lshl_add_u64 v[62:63], s[38:39], 0, v[62:63]
	v_lshlrev_b64 v[60:61], 15, v[60:61]
	v_lshl_add_u64 v[62:63], v[62:63], 0, v[64:65]
	v_lshl_add_u64 v[60:61], s[38:39], 0, v[60:61]
	v_lshl_add_u64 v[62:63], v[62:63], 0, v[102:103]
	v_lshl_add_u64 v[60:61], v[60:61], 0, v[64:65]
	v_lshl_add_u64 v[60:61], v[60:61], 0, v[102:103]
	global_load_dwordx4 v[66:69], v[62:63], off
	s_nop 0
	global_load_dwordx4 v[62:65], v[60:61], off

; #define LAS __attribute__((address_space(3)))
; __device__ __forceinline__ size_t tmo(int row, int ct, int nct) { return ((size_t)(row >> 8) * nct + ct) * 32768 + (size_t)(row & 255) * 128; }
; __device__ __forceinline__ void attn_b_unit(LAS unsigned char* lds, const bf16* Z, bf16* Y, int unit) {
;     const int tid = threadIdx.x, lane = tid & 63, wid = tid >> 6, lq = lane & 15, g = lane >> 4;
;     const int rp = unit & 63, h = (unit >> 6) & 7, b = unit >> 9;
;     const size_t tok0 = (size_t)b * SEQ;
;     const int R0 = clampi(2 * rp - 4, 0, 120);
;     LAS unsigned char* Kl = lds + B_KOFF; LAS unsigned char* Vl = lds + B_VOFF; LAS float* T = (LAS float*)(lds + B_TOFF);
;     const int rq = 2 * rp + (wid >> 2), cb = wid & 3, c = 16 * cb + lq;
;     const int r0q = clampi(rq - 4, 0, 120), kc0 = clampi(16 * cb - 8, 0, 32), cs = clampi(c - 8, 0, 48);
;     const size_t qtok = tok0 + (size_t)rq * 64 + c;
;     const unsigned char* qp = (const unsigned char*)Z + tmo((int)qtok, Z_QB / 64 + h, ZLD / 64) + 16 * g;
;     const bf16x8 qf0 = *(const bf16x8*)qp, qf1 = *(const bf16x8*)(qp + 64);
;     float m0 = -1e30f, l0 = 0.f, m1 = -1e30f, l1 = 0.f;
;     f32x4 O0[4], O1[4];
; #pragma unroll
;     for (int d = 0; d < 4; ++d) { O0[d] = (f32x4){0.f, 0.f, 0.f, 0.f}; O1[d] = (f32x4){0.f, 0.f, 0.f, 0.f}; }
;     const int kcl = kc0 + 4 * g;
;     const int tb = 16 + (kcl - c + 15);
;     const int Rb = (r0q - R0) * 64 + kc0;
;     const LAS unsigned char* kp0 = Kl + swz(Rb + lq, g); const LAS unsigned char* kp1 = Kl + swz(Rb + lq, 4 + g);
;     const LAS unsigned char* vp[4];
;     { const int i = lane & 15, rq4 = i >> 2, p = i & 3;
; #pragma unroll
;       for (int db = 0; db < 4; ++db) vp[db] = Vl + swz(Rb + 4 * g + rq4, 2 * db + (p >> 1)) + 8 * (p & 1); }
;     const LAS float* T0 = T + tb + (r0q - rq + 7) * 32;
;     const LAS float* tpa[4]; const LAS float* tpb[4];
; #pragma unroll
;     for (int r = 0; r < 4; ++r) { const int kca = kcl + r, kcb = kca + 16;
;         tpa[r] = (kca >= cs && kca <= cs + 15) ? T0 + r : T + B_TREAL; tpb[r] = (kcb >= cs && kcb <= cs + 15) ? T0 + 16 + r : T + B_TREAL; }
.LBB0_278:
	s_or_b64 exec, exec, s[10:11]
	v_lshlrev_b32_e32 v79, 7, v78
	v_xor_b32_e32 v78, v78, v218
	v_lshlrev_b32_e32 v78, 4, v78
	s_movk_i32 s0, 0x70
	v_and_or_b32 v78, v78, s0, v79
	v_add_u32_e32 v79, 0x200, v218
	v_add_u32_e32 v82, 0x600, v218
	v_add_u32_e32 v84, 0xa00, v218
	v_add_u32_e32 v86, 0xe00, v218
	v_lshrrev_b32_e32 v80, 3, v79
	v_lshrrev_b32_e32 v82, 3, v82
	v_lshrrev_b32_e32 v84, 3, v84
	v_lshrrev_b32_e32 v86, 3, v86
	v_lshlrev_b32_e32 v81, 7, v80
	v_xor_b32_e32 v80, v80, v218
	v_lshlrev_b32_e32 v83, 7, v82
	v_xor_b32_e32 v82, v82, v218
	v_lshlrev_b32_e32 v85, 7, v84
	v_xor_b32_e32 v84, v84, v218
	v_lshlrev_b32_e32 v87, 7, v86
	v_xor_b32_e32 v86, v86, v218
	v_lshlrev_b32_e32 v80, 4, v80
	v_lshlrev_b32_e32 v82, 4, v82
	v_lshlrev_b32_e32 v84, 4, v84
	v_lshlrev_b32_e32 v86, 4, v86
	v_mad_i32_i24 v112, v61, 31, v59
	v_lshrrev_b32_e32 v59, 2, v218
	v_and_or_b32 v80, v80, s0, v81
	v_and_or_b32 v82, v82, s0, v83
	v_and_or_b32 v84, v84, s0, v85
	v_and_or_b32 v86, v86, s0, v87
	s_movk_i32 s0, 0x320
	v_cmp_eq_u32_e64 s[8:9], 15, v60
	v_and_b32_e32 v60, 48, v59
	v_cmp_lt_u32_e64 s[4:5], 31, v218
	v_cmp_gt_u32_e64 s[22:23], s0, v218
	s_movk_i32 s0, 0x120
	v_cmp_lt_i32_e64 s[6:7], 14, v61
	v_add_u32_e32 v59, -8, v60
	v_cndmask_b32_e64 v108, 0, v58, s[4:5]
	v_cmp_gt_u32_e64 s[4:5], s0, v218
	s_or_b64 s[0:1], s[8:9], s[6:7]
	v_and_b32_e32 v113, 15, v218
	v_bfe_u32 v114, v218, 4, 2
	v_min_u32_e32 v61, 32, v59
	v_cmp_ne_u32_e64 s[8:9], 0, v60
	v_or_b32_e32 v116, v60, v113
	v_lshlrev_b32_e32 v60, 2, v114
	v_cndmask_b32_e64 v117, 0, v61, s[8:9]
	v_bfe_u32 v87, v218, 2, 2
	s_add_i32 s3, 0, 0x24000
	v_subrev_co_u32_e64 v59, s[6:7], 8, v116
	v_add_u32_e32 v61, v117, v60
	v_or_b32_e32 v119, v60, v87
	v_lshlrev_b32_e32 v60, 3, v218
	v_lshl_add_u32 v111, v79, 2, s3
	s_xor_b64 s[28:29], s[0:1], -1
	v_min_u32_e32 v79, 48, v59
	v_and_b32_e32 v60, 8, v60
	s_add_i32 s0, 0, 0x12000
	v_add_u32_e32 v120, s0, v60
	v_cndmask_b32_e64 v60, v79, 0, s[6:7]
	v_sub_u32_e32 v79, v61, v116
	v_lshl_add_u32 v121, v79, 2, s3
	v_add_u32_e32 v79, 15, v60
	v_add_u32_e32 v87, 16, v61
	v_cmp_lt_u32_e64 s[6:7], v61, v60
	v_cmp_gt_u32_e64 s[8:9], v61, v79
	s_or_b64 s[6:7], s[6:7], s[8:9]
	v_cmp_lt_u32_e64 s[8:9], v87, v60
	v_cmp_gt_u32_e64 s[10:11], v87, v79
	v_or_b32_e32 v87, 1, v61
	s_or_b64 s[8:9], s[8:9], s[10:11]
	v_add_u32_e32 v88, 17, v61
	v_cmp_lt_u32_e64 s[10:11], v87, v60
	v_cmp_ge_u32_e64 s[12:13], v61, v79
	s_or_b64 s[10:11], s[10:11], s[12:13]
	v_cmp_lt_u32_e64 s[12:13], v88, v60
	v_cmp_gt_u32_e64 s[14:15], v88, v79
	v_or_b32_e32 v87, 2, v61
	s_or_b64 s[12:13], s[12:13], s[14:15]
	v_add_u32_e32 v88, 18, v61
	v_cmp_lt_u32_e64 s[14:15], v87, v60
	v_cmp_gt_u32_e64 s[16:17], v87, v79
	s_or_b64 s[14:15], s[14:15], s[16:17]
	v_cmp_lt_u32_e64 s[16:17], v88, v60
	v_cmp_gt_u32_e64 s[18:19], v88, v79
	v_or_b32_e32 v87, 3, v61
	s_or_b64 s[16:17], s[16:17], s[18:19]
	v_add_u32_e32 v61, 19, v61
	v_cmp_lt_u32_e64 s[18:19], v87, v60
	v_cmp_gt_u32_e64 s[20:21], v87, v79
	s_or_b64 s[18:19], s[18:19], s[20:21]
	v_cmp_lt_u32_e64 s[20:21], v61, v60
	v_cmp_gt_u32_e64 s[24:25], v61, v79
	v_add_u32_e32 v60, 0xfffffde0, v218
	s_movk_i32 s1, 0xfdef
	v_or_b32_e32 v81, 0x4000, v78
	v_or_b32_e32 v83, 0x8000, v78
	v_or_b32_e32 v85, 0xc000, v78
	v_or_b32_e32 v109, 0x10000, v78
	v_mov_b32_e32 v59, 0
	s_or_b64 s[20:21], s[20:21], s[24:25]
	v_cmp_lt_u32_e64 s[24:25], s1, v60
	s_mov_b32 s27, 0
	v_lshl_add_u32 v110, v218, 2, s3
	v_lshrrev_b32_e32 v115, 8, v218
	v_lshlrev_b32_e32 v104, 4, v114
	v_mov_b32_e32 v105, v59
	v_or_b32_e32 v118, 4, v114
	s_and_b64 s[24:25], s[24:25], s[28:29]
	v_cndmask_b32_e32 v122, 0, v58, vcc
	s_lshl_b32 s1, s90, 4
	s_lshl_b32 s3, s90, 1
	v_add_u32_e32 v123, 0, v78
	v_add_u32_e32 v124, s0, v78
	v_add_u32_e32 v125, 0, v80
	v_add_u32_e32 v126, s0, v80
	v_add_u32_e32 v127, s0, v81
	v_add_u32_e32 v128, 0, v82
	v_add_u32_e32 v129, s0, v82
	v_add_u32_e32 v130, s0, v83
	v_add_u32_e32 v131, 0, v84
	v_add_u32_e32 v132, s0, v84
	v_add_u32_e32 v133, s0, v85
	v_add_u32_e32 v138, 0, v86
	v_add_u32_e32 v139, s0, v86
	v_add_u32_e32 v140, 0, v109
	s_movk_i32 s52, 0x79
	s_add_i32 s53, 0, 0x24880
	s_mov_b32 s54, 0xf149f2ca
	s_mov_b64 s[28:29], 0x40000
	s_mov_b32 s72, s89
	s_mov_b32 s85, 0
	s_mov_b32 s88, 1
	s_branch .LBB0_281

; __device__ __forceinline__ void attn_b_unit(LAS unsigned char* lds, const bf16* Z, bf16* Y, int unit) {
;     const int tid = threadIdx.x, lane = tid & 63, wid = tid >> 6, lq = lane & 15, g = lane >> 4;
;     const int rp = unit & 63, h = (unit >> 6) & 7, b = unit >> 9;
;     const size_t tok0 = (size_t)b * SEQ;
;     const int R0 = clampi(2 * rp - 4, 0, 120);
;     LAS unsigned char* Kl = lds + B_KOFF; LAS unsigned char* Vl = lds + B_VOFF; LAS float* T = (LAS float*)(lds + B_TOFF);
;     const int rq = 2 * rp + (wid >> 2), cb = wid & 3, c = 16 * cb + lq;
;     const int r0q = clampi(rq - 4, 0, 120), kc0 = clampi(16 * cb - 8, 0, 32), cs = clampi(c - 8, 0, 48);
;     const size_t qtok = tok0 + (size_t)rq * 64 + c;
;     const unsigned char* qp = (const unsigned char*)Z + tmo((int)qtok, Z_QB / 64 + h, ZLD / 64) + 16 * g;
;     const bf16x8 qf0 = *(const bf16x8*)qp, qf1 = *(const bf16x8*)(qp + 64);
;     float m0 = -1e30f, l0 = 0.f, m1 = -1e30f, l1 = 0.f;
;     f32x4 O0[4], O1[4];
; #pragma unroll
;     for (int d = 0; d < 4; ++d) { O0[d] = (f32x4){0.f, 0.f, 0.f, 0.f}; O1[d] = (f32x4){0.f, 0.f, 0.f, 0.f}; }
;     const int kcl = kc0 + 4 * g;
;     const int tb = 16 + (kcl - c + 15);
;     const int Rb = (r0q - R0) * 64 + kc0;
;     const LAS unsigned char* kp0 = Kl + swz(Rb + lq, g); const LAS unsigned char* kp1 = Kl + swz(Rb + lq, 4 + g);
;     const LAS unsigned char* vp[4];
;     { const int i = lane & 15, rq4 = i >> 2, p = i & 3;
; #pragma unroll
;       for (int db = 0; db < 4; ++db) vp[db] = Vl + swz(Rb + 4 * g + rq4, 2 * db + (p >> 1)) + 8 * (p & 1); }
;     const LAS float* T0 = T + tb + (r0q - rq + 7) * 32;
;     const LAS float* tpa[4]; const LAS float* tpb[4];
; #pragma unroll
;     for (int r = 0; r < 4; ++r) { const int kca = kcl + r, kcb = kca + 16;
;         tpa[r] = (kca >= cs && kca <= cs + 15) ? T0 + r : T + B_TREAL; tpb[r] = (kcb >= cs && kcb <= cs + 15) ? T0 + 16 + r : T + B_TREAL; }
; #pragma unroll
;     for (int st = 0; st < 4; ++st) {
;         const int offA = st * 8192, offB = offA + 4 * 8192;
;         f32x4 SA0, SA1, SB0, SB1;
;         qk_at(kp0, kp1, offA, qf0, qf1, SA0, SA1);
;         qk_at(kp0, kp1, offB, qf0, qf1, SB0, SB1);
; #pragma unroll
;         for (int r = 0; r < 4; ++r) {
;             SA0[r] += tpa[r][st * 32]; SA1[r] += tpb[r][st * 32]; SB0[r] += tpa[r][st * 32 + 128]; SB1[r] += tpb[r][st * 32 + 128];
;         }
.LBB0_280:
	v_readlane_b32 s26, v246, 7
	s_nop 3
	s_lshr_b32 s26, s26, 2
	s_and_b32 s51, s58, 0x7e
	s_add_i32 s50, s51, s26
	s_sub_i32 s73, s50, 4
	s_max_i32 s73, s73, 0
	s_min_i32 s73, s73, 0x78
	s_sub_i32 s74, s73, s50
	s_lshl_b32 s74, s74, 7
	s_sub_i32 s75, s73, s84
	s_mul_i32 s76, s75, 57
	s_lshr_b32 s76, s76, 9
	s_mul_i32 s76, s76, 9
	s_sub_i32 s75, s75, s76
	s_lshl_b32 s76, s75, 13
	s_add_i32 s77, s76, 0x2000
	s_cmp_eq_u32 s77, 0x12000
	s_cselect_b32 s77, 0, s77
	s_add_i32 s78, s77, 0x2000
	s_cmp_eq_u32 s78, 0x12000
	s_cselect_b32 s78, 0, s78
	s_add_i32 s79, s78, 0x2000
	s_cmp_eq_u32 s79, 0x12000
	s_cselect_b32 s79, 0, s79
	s_add_i32 s80, s79, 0x2000
	s_cmp_eq_u32 s80, 0x12000
	s_cselect_b32 s80, 0, s80
	s_add_i32 s81, s80, 0x2000
	s_cmp_eq_u32 s81, 0x12000
	s_cselect_b32 s81, 0, s81
	s_add_i32 s82, s81, 0x2000
	s_cmp_eq_u32 s82, 0x12000
	s_cselect_b32 s82, 0, s82
	s_add_i32 s83, s82, 0x2000
	s_cmp_eq_u32 s83, 0x12000
	s_cselect_b32 s83, 0, s83
	v_add_u32_e32 v61, s51, v115
	s_and_b32 s26, s59, 0xffffe000
	v_lshlrev_b32_e32 v58, 6, v61
	v_add_u32_e32 v60, s26, v58
	s_bfe_u32 s50, s72, 0x30006
	v_ashrrev_i32_e32 v60, 8, v60
	v_or_b32_e32 v58, v58, v116
	v_lshlrev_b32_e32 v58, 7, v58
	v_and_b32_e32 v58, 0x7f80, v58
	v_add_u32_e32 v101, v117, v113
	v_add_u32_e32 v216, v117, v119
	v_bitop3_b32 v100, v101, v114, 7 bitop3:0x6c
	v_lshlrev_b32_e32 v217, 7, v101
	v_lshlrev_b32_e32 v100, 4, v100
	v_add_u32_e32 v61, s74, v121
	v_add3_u32 v86, 0, v100, v217
	v_bitop3_b32 v100, v101, v118, 7 bitop3:0x6c
	v_lshlrev_b32_e32 v100, 4, v100
	v_add3_u32 v87, 0, v100, v217
	v_add_u32_e32 v100, 0x3fc, v61
	v_add_u32_e32 v101, 0x43c, v61
	v_cndmask_b32_e64 v92, v100, v101, s[6:7]
	v_add_u32_e32 v100, 0x400, v61
	v_add_u32_e32 v101, 0x440, v61
	v_cndmask_b32_e64 v93, v100, v101, s[10:11]
	v_add_u32_e32 v100, 0x404, v61
	v_add_u32_e32 v101, 0x444, v61
	v_cndmask_b32_e64 v94, v100, v101, s[14:15]
	v_add_u32_e32 v100, 0x408, v61
	v_add_u32_e32 v101, 0x448, v61
	v_cndmask_b32_e64 v95, v100, v101, s[18:19]
	v_lshl_add_u32 v217, v216, 7, v120
	v_bitop3_b32 v100, v216, v134, 7 bitop3:0x6c
	v_lshl_add_u32 v88, v100, 4, v217
	v_bitop3_b32 v100, v216, v135, 7 bitop3:0x6c
	v_lshl_add_u32 v89, v100, 4, v217
	v_bitop3_b32 v100, v216, v136, 7 bitop3:0x6c
	v_lshl_add_u32 v90, v100, 4, v217
	v_bitop3_b32 v100, v216, v137, 7 bitop3:0x6c
	v_lshl_add_u32 v91, v100, 4, v217
	s_lshl_b32 s26, s50, 15
	v_ashrrev_i32_e32 v61, 31, v60
	v_lshlrev_b64 v[60:61], 19, v[60:61]
	v_lshl_add_u64 v[60:61], s[40:41], 0, v[60:61]
	v_lshl_add_u64 v[60:61], v[60:61], 0, s[26:27]
	v_lshl_add_u64 v[60:61], v[60:61], 0, v[58:59]
	v_lshlrev_b32_e32 v58, 1, v104
	v_lshl_add_u64 v[60:61], v[60:61], 0, v[58:59]
	v_lshl_add_u64 v[60:61], v[60:61], 0, s[28:29]
	s_lshl_b32 s58, s55, 1
	s_lshl_b32 s59, s55, 4
	s_mov_b32 s72, s55
	ds_read_b32 v156, v92 offset:0
	ds_read_b32 v157, v93 offset:0
	ds_read_b32 v158, v94 offset:0
	ds_read_b32 v159, v95 offset:0
	v_add_u32_e32 v100, s76, v86
	v_add_u32_e32 v101, s76, v87
	ds_read_b128 v[204:207], v100
	ds_read_b128 v[208:211], v100 offset:2048
	ds_read_b128 v[212:215], v101
	ds_read_b128 v[220:223], v101 offset:2048
	s_waitcnt lgkmcnt(7)
	ds_read_b32 v160, v92 offset:128
	ds_read_b32 v161, v93 offset:128
	ds_read_b32 v162, v94 offset:128
	ds_read_b32 v163, v95 offset:128
	v_add_u32_e32 v100, s77, v86
	v_add_u32_e32 v101, s77, v87
	ds_read_b128 v[224:227], v100
	ds_read_b128 v[228:231], v100 offset:2048
	ds_read_b128 v[232:235], v101
	ds_read_b128 v[236:239], v101 offset:2048
	s_waitcnt vmcnt(4)
	s_waitcnt lgkmcnt(11)
	v_mfma_f32_16x16x32_bf16 v[188:191], v[204:207], v[82:85], v[156:159]
	s_waitcnt lgkmcnt(10)
	v_mfma_f32_16x16x32_bf16 v[192:195], v[208:211], v[82:85], v[156:159]
	s_waitcnt lgkmcnt(9)
	v_mfma_f32_16x16x32_bf16 v[188:191], v[212:215], v[78:81], v[188:191]
	s_waitcnt lgkmcnt(8)
	v_mfma_f32_16x16x32_bf16 v[192:195], v[220:223], v[78:81], v[192:195]
	s_waitcnt lgkmcnt(7)
	ds_read_b32 v164, v92 offset:256
	ds_read_b32 v165, v93 offset:256
	ds_read_b32 v166, v94 offset:256
	ds_read_b32 v167, v95 offset:256
	v_add_u32_e32 v100, s78, v86
	v_add_u32_e32 v101, s78, v87
	ds_read_b128 v[240:243], v100
	ds_read_b128 v[144:147], v100 offset:2048
	ds_read_b128 v[148:151], v101
	ds_read_b128 v[152:155], v101 offset:2048
	s_waitcnt lgkmcnt(11)
	v_mfma_f32_16x16x32_bf16 v[196:199], v[224:227], v[82:85], v[160:163]
	s_waitcnt lgkmcnt(10)
	v_mfma_f32_16x16x32_bf16 v[200:203], v[228:231], v[82:85], v[160:163]
	s_waitcnt lgkmcnt(9)
	v_mfma_f32_16x16x32_bf16 v[196:199], v[232:235], v[78:81], v[196:199]
	s_waitcnt lgkmcnt(8)
	v_mfma_f32_16x16x32_bf16 v[200:203], v[236:239], v[78:81], v[200:203]
	s_waitcnt lgkmcnt(7)
	ds_read_b32 v168, v92 offset:384
	ds_read_b32 v169, v93 offset:384
	ds_read_b32 v170, v94 offset:384
	ds_read_b32 v171, v95 offset:384
	v_add_u32_e32 v100, s79, v86
	v_add_u32_e32 v101, s79, v87
	ds_read_b128 v[204:207], v100
	ds_read_b128 v[208:211], v100 offset:2048
	ds_read_b128 v[212:215], v101
	ds_read_b128 v[220:223], v101 offset:2048
	v_cndmask_b32_e64 v156, v188, v192, s[6:7]
	v_cndmask_b32_e64 v157, v189, v193, s[10:11]
	v_cndmask_b32_e64 v158, v190, v194, s[14:15]
	v_cndmask_b32_e64 v159, v191, v195, s[18:19]
	s_waitcnt lgkmcnt(11)
	v_mfma_f32_16x16x32_bf16 v[188:191], v[240:243], v[82:85], v[164:167]
	s_waitcnt lgkmcnt(10)
	v_mfma_f32_16x16x32_bf16 v[192:195], v[144:147], v[82:85], v[164:167]
	s_waitcnt lgkmcnt(9)
	v_mfma_f32_16x16x32_bf16 v[188:191], v[148:151], v[78:81], v[188:191]
	s_waitcnt lgkmcnt(8)
	v_mfma_f32_16x16x32_bf16 v[192:195], v[152:155], v[78:81], v[192:195]
	s_waitcnt lgkmcnt(7)
; __device__ __forceinline__ void attn_b_unit(LAS unsigned char* lds, const bf16* Z, bf16* Y, int unit) {
;     ...
;     for (int st = 0; st < 4; ++st) {
;         const int offA = st * 8192, offB = offA + 4 * 8192;
;         f32x4 SA0, SA1, SB0, SB1;
;         qk_at(kp0, kp1, offA, qf0, qf1, SA0, SA1);
;         qk_at(kp0, kp1, offB, qf0, qf1, SB0, SB1);
; #pragma unroll
;         for (int r = 0; r < 4; ++r) {
;             SA0[r] += tpa[r][st * 32]; SA1[r] += tpb[r][st * 32]; SB0[r] += tpa[r][st * 32 + 128]; SB1[r] += tpb[r][st * 32 + 128];
;         }
;         softmax_step(SA0, SA1, m0, l0, O0);
;         softmax_step(SB0, SB1, m1, l1, O1);
;         pv_at(vp, offA, SA0, SA1, O0);
;         pv_at(vp, offB, SB0, SB1, O1);
;     }
	ds_read_b32 v172, v92 offset:512
	ds_read_b32 v173, v93 offset:512
	ds_read_b32 v174, v94 offset:512
	ds_read_b32 v175, v95 offset:512
	v_add_u32_e32 v100, s80, v86
	v_add_u32_e32 v101, s80, v87
	ds_read_b128 v[224:227], v100
	ds_read_b128 v[228:231], v100 offset:2048
	ds_read_b128 v[232:235], v101
	ds_read_b128 v[236:239], v101 offset:2048
	v_cndmask_b32_e64 v160, v196, v200, s[6:7]
	v_cndmask_b32_e64 v161, v197, v201, s[10:11]
	v_cndmask_b32_e64 v162, v198, v202, s[14:15]
	v_cndmask_b32_e64 v163, v199, v203, s[18:19]
	s_waitcnt lgkmcnt(11)
	v_mfma_f32_16x16x32_bf16 v[196:199], v[204:207], v[82:85], v[168:171]
	s_waitcnt lgkmcnt(10)
	v_mfma_f32_16x16x32_bf16 v[200:203], v[208:211], v[82:85], v[168:171]
	s_waitcnt lgkmcnt(9)
	v_mfma_f32_16x16x32_bf16 v[196:199], v[212:215], v[78:81], v[196:199]
	s_waitcnt lgkmcnt(8)
	v_mfma_f32_16x16x32_bf16 v[200:203], v[220:223], v[78:81], v[200:203]
	s_waitcnt lgkmcnt(7)
	ds_read_b32 v176, v92 offset:640
	ds_read_b32 v177, v93 offset:640
	ds_read_b32 v178, v94 offset:640
	ds_read_b32 v179, v95 offset:640
	v_add_u32_e32 v100, s81, v86
	v_add_u32_e32 v101, s81, v87
	ds_read_b128 v[240:243], v100
	ds_read_b128 v[144:147], v100 offset:2048
	ds_read_b128 v[148:151], v101
	ds_read_b128 v[152:155], v101 offset:2048
	v_cndmask_b32_e64 v164, v188, v192, s[6:7]
	v_cndmask_b32_e64 v165, v189, v193, s[10:11]
	v_cndmask_b32_e64 v166, v190, v194, s[14:15]
	v_cndmask_b32_e64 v167, v191, v195, s[18:19]
	s_waitcnt lgkmcnt(11)
	v_mfma_f32_16x16x32_bf16 v[188:191], v[224:227], v[82:85], v[172:175]
	s_waitcnt lgkmcnt(10)
	v_mfma_f32_16x16x32_bf16 v[192:195], v[228:231], v[82:85], v[172:175]
	s_waitcnt lgkmcnt(9)
	v_mfma_f32_16x16x32_bf16 v[188:191], v[232:235], v[78:81], v[188:191]
	s_waitcnt lgkmcnt(8)
	v_mfma_f32_16x16x32_bf16 v[192:195], v[236:239], v[78:81], v[192:195]
	s_waitcnt lgkmcnt(7)
	ds_read_b32 v180, v92 offset:768
	ds_read_b32 v181, v93 offset:768
	ds_read_b32 v182, v94 offset:768
	ds_read_b32 v183, v95 offset:768
	v_add_u32_e32 v100, s82, v86
	v_add_u32_e32 v101, s82, v87
	ds_read_b128 v[204:207], v100
	ds_read_b128 v[208:211], v100 offset:2048
	ds_read_b128 v[212:215], v101
	ds_read_b128 v[220:223], v101 offset:2048
	v_cndmask_b32_e64 v168, v196, v200, s[6:7]
	v_cndmask_b32_e64 v169, v197, v201, s[10:11]
	v_cndmask_b32_e64 v170, v198, v202, s[14:15]
	v_cndmask_b32_e64 v171, v199, v203, s[18:19]
	s_waitcnt lgkmcnt(11)
	v_mfma_f32_16x16x32_bf16 v[196:199], v[240:243], v[82:85], v[176:179]
	s_waitcnt lgkmcnt(10)
	v_mfma_f32_16x16x32_bf16 v[200:203], v[144:147], v[82:85], v[176:179]
	s_waitcnt lgkmcnt(9)
	v_mfma_f32_16x16x32_bf16 v[196:199], v[148:151], v[78:81], v[196:199]
	s_waitcnt lgkmcnt(8)
	v_mfma_f32_16x16x32_bf16 v[200:203], v[152:155], v[78:81], v[200:203]
	s_waitcnt lgkmcnt(7)
	ds_read_b32 v184, v92 offset:896
	ds_read_b32 v185, v93 offset:896
	ds_read_b32 v186, v94 offset:896
	ds_read_b32 v187, v95 offset:896
	v_add_u32_e32 v100, s83, v86
	v_add_u32_e32 v101, s83, v87
	ds_read_b128 v[224:227], v100
	ds_read_b128 v[228:231], v100 offset:2048
	ds_read_b128 v[232:235], v101
	ds_read_b128 v[236:239], v101 offset:2048
	v_cndmask_b32_e64 v172, v188, v192, s[6:7]
	v_cndmask_b32_e64 v173, v189, v193, s[10:11]
	v_cndmask_b32_e64 v174, v190, v194, s[14:15]
	v_cndmask_b32_e64 v175, v191, v195, s[18:19]
	s_waitcnt lgkmcnt(11)
	v_mfma_f32_16x16x32_bf16 v[188:191], v[204:207], v[82:85], v[180:183]
	s_waitcnt lgkmcnt(10)
	v_mfma_f32_16x16x32_bf16 v[192:195], v[208:211], v[82:85], v[180:183]
	s_waitcnt lgkmcnt(9)
	v_mfma_f32_16x16x32_bf16 v[188:191], v[212:215], v[78:81], v[188:191]
	s_waitcnt lgkmcnt(8)
	v_mfma_f32_16x16x32_bf16 v[192:195], v[220:223], v[78:81], v[192:195]
	v_cndmask_b32_e64 v176, v196, v200, s[6:7]
	v_cndmask_b32_e64 v177, v197, v201, s[10:11]
	v_cndmask_b32_e64 v178, v198, v202, s[14:15]
	v_cndmask_b32_e64 v179, v199, v203, s[18:19]
	s_waitcnt lgkmcnt(3)
	v_mfma_f32_16x16x32_bf16 v[196:199], v[224:227], v[82:85], v[184:187]
	s_waitcnt lgkmcnt(2)
	v_mfma_f32_16x16x32_bf16 v[200:203], v[228:231], v[82:85], v[184:187]
	s_waitcnt lgkmcnt(1)
	v_mfma_f32_16x16x32_bf16 v[196:199], v[232:235], v[78:81], v[196:199]
	s_waitcnt lgkmcnt(0)
	v_mfma_f32_16x16x32_bf16 v[200:203], v[236:239], v[78:81], v[200:203]
	v_cndmask_b32_e64 v180, v188, v192, s[6:7]
	v_cndmask_b32_e64 v181, v189, v193, s[10:11]
	v_cndmask_b32_e64 v182, v190, v194, s[14:15]
	v_cndmask_b32_e64 v183, v191, v195, s[18:19]
	v_add_u32_e32 v219, s76, v88
	v_add_u32_e32 v86, s76, v89
	v_add_u32_e32 v87, s76, v90
	v_add_u32_e32 v92, s76, v91
	ds_read_b64_tr_b16 v[212:213], v219
	ds_read_b64_tr_b16 v[214:215], v219 offset:2048
	ds_read_b64_tr_b16 v[220:221], v86
	ds_read_b64_tr_b16 v[222:223], v86 offset:2048
	ds_read_b64_tr_b16 v[224:225], v87
	ds_read_b64_tr_b16 v[226:227], v87 offset:2048
	ds_read_b64_tr_b16 v[228:229], v92
	ds_read_b64_tr_b16 v[230:231], v92 offset:2048
	v_mov_b32_e32 v100, 0xffff
	v_mov_b32_e32 v101, 0xffff0000
	v_cndmask_b32_e64 v96, v100, 0, s[6:7]
	v_cndmask_b32_e64 v216, v101, 0, s[10:11]
	v_cndmask_b32_e64 v97, v100, 0, s[14:15]
	v_cndmask_b32_e64 v217, v101, 0, s[18:19]
	v_cndmask_b32_e64 v184, v196, v200, s[6:7]
	v_cndmask_b32_e64 v185, v197, v201, s[10:11]
	v_cndmask_b32_e64 v186, v198, v202, s[14:15]
	v_cndmask_b32_e64 v187, v199, v203, s[18:19]
	v_or_b32_e32 v96, v96, v216
	v_or_b32_e32 v97, v97, v217
	v_not_b32_e32 v98, v96
	v_not_b32_e32 v99, v97
	s_waitcnt lgkmcnt(7)
; __device__ __forceinline__ void softmax_step(f32x4& s0, f32x4& s1, float& m, float& l, f32x4 (&O)[4]) {
;     float t = fmaxf(fmaxf(fmaxf(s0[0], s0[1]), fmaxf(s0[2], s0[3])), fmaxf(fmaxf(s1[0], s1[1]), fmaxf(s1[2], s1[3])));
;     t = xrow16_max(t);
;     const float mn = fmaxf(m, t), alpha = __builtin_amdgcn_exp2f(m - mn);
;     m = mn;
; #pragma unroll
;     for (int k = 0; k < 4; ++k) { s0[k] = __builtin_amdgcn_exp2f(s0[k] - mn); s1[k] = __builtin_amdgcn_exp2f(s1[k] - mn); }
;     l = l * alpha + ((s0[0] + s0[1]) + (s0[2] + s0[3])) + ((s1[0] + s1[1]) + (s1[2] + s1[3]));
; #pragma unroll
;     for (int db = 0; db < 4; ++db) O[db] *= alpha;
; }
; __device__ __forceinline__ void attn_b_unit(LAS unsigned char* lds, const bf16* Z, bf16* Y, int unit) {
;     ...
;     for (int st = 0; st < 4; ++st) {
;         const int offA = st * 8192, offB = offA + 4 * 8192;
;         f32x4 SA0, SA1, SB0, SB1;
;         qk_at(kp0, kp1, offA, qf0, qf1, SA0, SA1);
;         qk_at(kp0, kp1, offB, qf0, qf1, SB0, SB1);
; #pragma unroll
;         for (int r = 0; r < 4; ++r) {
;             SA0[r] += tpa[r][st * 32]; SA1[r] += tpb[r][st * 32]; SB0[r] += tpa[r][st * 32 + 128]; SB1[r] += tpb[r][st * 32 + 128];
;         }
;         softmax_step(SA0, SA1, m0, l0, O0);
;         softmax_step(SB0, SB1, m1, l1, O1);
;         pv_at(vp, offA, SA0, SA1, O0);
;         pv_at(vp, offB, SB0, SB1, O1);
;     }
	v_add_u32_e32 v219, s77, v88
	v_add_u32_e32 v86, s77, v89
	v_add_u32_e32 v87, s77, v90
	v_add_u32_e32 v92, s77, v91
	ds_read_b64_tr_b16 v[232:233], v219
	ds_read_b64_tr_b16 v[234:235], v219 offset:2048
	ds_read_b64_tr_b16 v[236:237], v86
	ds_read_b64_tr_b16 v[238:239], v86 offset:2048
	ds_read_b64_tr_b16 v[240:241], v87
	ds_read_b64_tr_b16 v[242:243], v87 offset:2048
	ds_read_b64_tr_b16 v[144:145], v92
	ds_read_b64_tr_b16 v[146:147], v92 offset:2048
	v_max3_f32 v142, v156, v157, v158
	v_max3_f32 v143, v164, v165, v166
	v_max3_f32 v216, v172, v173, v174
	v_max3_f32 v217, v180, v181, v182
	v_max3_f32 v142, v142, v159, v160
	v_max3_f32 v143, v143, v167, v168
	v_max3_f32 v216, v216, v175, v176
	v_max3_f32 v217, v217, v183, v184
	v_max3_f32 v142, v142, v161, v162
	v_max3_f32 v143, v143, v169, v170
	v_max3_f32 v216, v216, v177, v178
	v_max3_f32 v217, v217, v185, v186
	v_max_f32_e32 v142, v142, v163
	v_max_f32_e32 v143, v143, v171
	v_max_f32_e32 v216, v216, v179
	v_max_f32_e32 v217, v217, v187
	v_max3_f32 v244, v142, v143, v216
	v_max_f32_e32 v244, v244, v217
	v_mov_b32_e32 v100, v244
	s_nop 1
	v_permlane16_swap_b32_e32 v244, v100
	v_max_f32_e32 v244, v244, v100
	v_mov_b32_e32 v100, v244
	s_nop 1
	v_permlane32_swap_b32_e32 v244, v100
	v_max3_f32 v244, v244, v100, s54
	v_pk_add_f32 v[156:157], v[156:157], v[244:245] op_sel_hi:[1,0] neg_lo:[0,1] neg_hi:[0,1]
	v_pk_add_f32 v[158:159], v[158:159], v[244:245] op_sel_hi:[1,0] neg_lo:[0,1] neg_hi:[0,1]
	v_pk_add_f32 v[160:161], v[160:161], v[244:245] op_sel_hi:[1,0] neg_lo:[0,1] neg_hi:[0,1]
	v_pk_add_f32 v[162:163], v[162:163], v[244:245] op_sel_hi:[1,0] neg_lo:[0,1] neg_hi:[0,1]
	v_pk_add_f32 v[164:165], v[164:165], v[244:245] op_sel_hi:[1,0] neg_lo:[0,1] neg_hi:[0,1]
	v_pk_add_f32 v[166:167], v[166:167], v[244:245] op_sel_hi:[1,0] neg_lo:[0,1] neg_hi:[0,1]
	v_pk_add_f32 v[168:169], v[168:169], v[244:245] op_sel_hi:[1,0] neg_lo:[0,1] neg_hi:[0,1]
	v_pk_add_f32 v[170:171], v[170:171], v[244:245] op_sel_hi:[1,0] neg_lo:[0,1] neg_hi:[0,1]
	v_pk_add_f32 v[172:173], v[172:173], v[244:245] op_sel_hi:[1,0] neg_lo:[0,1] neg_hi:[0,1]
	v_pk_add_f32 v[174:175], v[174:175], v[244:245] op_sel_hi:[1,0] neg_lo:[0,1] neg_hi:[0,1]
	v_pk_add_f32 v[176:177], v[176:177], v[244:245] op_sel_hi:[1,0] neg_lo:[0,1] neg_hi:[0,1]
	v_pk_add_f32 v[178:179], v[178:179], v[244:245] op_sel_hi:[1,0] neg_lo:[0,1] neg_hi:[0,1]
	v_pk_add_f32 v[180:181], v[180:181], v[244:245] op_sel_hi:[1,0] neg_lo:[0,1] neg_hi:[0,1]
	v_pk_add_f32 v[182:183], v[182:183], v[244:245] op_sel_hi:[1,0] neg_lo:[0,1] neg_hi:[0,1]
	v_pk_add_f32 v[184:185], v[184:185], v[244:245] op_sel_hi:[1,0] neg_lo:[0,1] neg_hi:[0,1]
	v_pk_add_f32 v[186:187], v[186:187], v[244:245] op_sel_hi:[1,0] neg_lo:[0,1] neg_hi:[0,1]
	v_exp_f32_e32 v156, v156
	v_exp_f32_e32 v157, v157
	v_exp_f32_e32 v158, v158
	v_exp_f32_e32 v159, v159
	v_exp_f32_e32 v160, v160
	v_exp_f32_e32 v161, v161
	v_exp_f32_e32 v162, v162
	v_exp_f32_e32 v163, v163
	v_exp_f32_e32 v164, v164
	v_exp_f32_e32 v165, v165
	v_exp_f32_e32 v166, v166
	v_exp_f32_e32 v167, v167
	v_exp_f32_e32 v168, v168
	v_exp_f32_e32 v169, v169
	v_exp_f32_e32 v170, v170
	v_exp_f32_e32 v171, v171
	v_exp_f32_e32 v172, v172
	v_exp_f32_e32 v173, v173
	v_exp_f32_e32 v174, v174
	v_exp_f32_e32 v175, v175
	v_exp_f32_e32 v176, v176
	v_exp_f32_e32 v177, v177
	v_exp_f32_e32 v178, v178
	v_exp_f32_e32 v179, v179
	v_exp_f32_e32 v180, v180
	v_exp_f32_e32 v181, v181
	v_exp_f32_e32 v182, v182
	v_exp_f32_e32 v183, v183
	v_exp_f32_e32 v184, v184
	v_exp_f32_e32 v185, v185
	v_exp_f32_e32 v186, v186
	v_exp_f32_e32 v187, v187
	v_pk_add_f32 v[148:149], v[156:157], v[158:159]
	v_pk_add_f32 v[150:151], v[164:165], v[166:167]
	v_pk_add_f32 v[152:153], v[172:173], v[174:175]
	v_pk_add_f32 v[154:155], v[180:181], v[182:183]
	v_pk_add_f32 v[148:149], v[148:149], v[160:161]
	v_pk_add_f32 v[150:151], v[150:151], v[168:169]
	v_pk_add_f32 v[152:153], v[152:153], v[176:177]
	v_pk_add_f32 v[154:155], v[154:155], v[184:185]
	v_pk_add_f32 v[148:149], v[148:149], v[162:163]
	v_pk_add_f32 v[150:151], v[150:151], v[170:171]
	v_pk_add_f32 v[152:153], v[152:153], v[178:179]
	v_pk_add_f32 v[154:155], v[154:155], v[186:187]
	v_pk_add_f32 v[148:149], v[148:149], v[150:151]
	v_pk_add_f32 v[152:153], v[152:153], v[154:155]
	v_pk_add_f32 v[148:149], v[148:149], v[152:153]
	v_add_f32_e32 v245, v148, v149
	v_cvt_pk_bf16_f32 v100, v156, v157
	v_cvt_pk_bf16_f32 v101, v158, v159
	v_and_b32_e32 v188, v100, v96
	v_and_b32_e32 v189, v101, v97
	v_and_b32_e32 v190, v100, v98
	v_and_b32_e32 v191, v101, v99
	s_nop 1
	s_waitcnt lgkmcnt(14)
	v_mfma_f32_16x16x32_bf16 v[196:199], v[212:215], v[188:191], 0
	s_waitcnt lgkmcnt(12)
	v_mfma_f32_16x16x32_bf16 v[200:203], v[220:223], v[188:191], 0
	s_waitcnt lgkmcnt(10)
	v_mfma_f32_16x16x32_bf16 v[204:207], v[224:227], v[188:191], 0
	s_waitcnt lgkmcnt(8)
	v_mfma_f32_16x16x32_bf16 v[208:211], v[228:231], v[188:191], 0
	v_cvt_pk_bf16_f32 v100, v160, v161
	v_cvt_pk_bf16_f32 v101, v162, v163
	v_and_b32_e32 v192, v100, v96
	v_and_b32_e32 v193, v101, v97
	v_and_b32_e32 v194, v100, v98
	v_and_b32_e32 v195, v101, v99
	s_waitcnt lgkmcnt(7)
	v_add_u32_e32 v219, s78, v88
	v_add_u32_e32 v86, s78, v89
	v_add_u32_e32 v87, s78, v90
	v_add_u32_e32 v92, s78, v91
	ds_read_b64_tr_b16 v[212:213], v219
	ds_read_b64_tr_b16 v[214:215], v219 offset:2048
	ds_read_b64_tr_b16 v[220:221], v86
	ds_read_b64_tr_b16 v[222:223], v86 offset:2048
	ds_read_b64_tr_b16 v[224:225], v87
	ds_read_b64_tr_b16 v[226:227], v87 offset:2048
	ds_read_b64_tr_b16 v[228:229], v92
	ds_read_b64_tr_b16 v[230:231], v92 offset:2048
	s_waitcnt lgkmcnt(14)
	v_mfma_f32_16x16x32_bf16 v[196:199], v[232:235], v[192:195], v[196:199]
	s_waitcnt lgkmcnt(12)
; #define LAS __attribute__((address_space(3)))
; __device__ __forceinline__ unsigned pk2(float lo, float hi) { return pg8::cvt_pk_bf16(lo, hi); }
; __device__ __forceinline__ s16x4 vtr(const LAS unsigned char* p) { return __builtin_bit_cast(s16x4, __builtin_amdgcn_ds_read_tr16_b64_v4i16((LAS s16x4*)p)); }
; #define MFMA16(a, b, c) __builtin_amdgcn_mfma_f32_16x16x32_bf16((a), (b), (c), 0, 0, 0)
; __device__ __forceinline__ void pv_at(const LAS unsigned char* const (&vp)[4], int off, const f32x4& P0, const f32x4& P1, f32x4 (&O)[4]) {
;     v4u pw; pw.x = pk2(P0[0], P0[1]); pw.y = pk2(P0[2], P0[3]); pw.z = pk2(P1[0], P1[1]); pw.w = pk2(P1[2], P1[3]);
;     const bf16x8 pb = __builtin_bit_cast(bf16x8, pw);
; #pragma unroll
;     for (int db = 0; db < 4; ++db) {
;         const s16x4 lo = vtr(vp[db] + off), hi = vtr(vp[db] + off + 2048);
;         const bf16x8 vt = (bf16x8){lo[0], lo[1], lo[2], lo[3], hi[0], hi[1], hi[2], hi[3]};
;         O[db] = MFMA16(vt, pb, O[db]);
;     }
; }
	v_mfma_f32_16x16x32_bf16 v[200:203], v[236:239], v[192:195], v[200:203]
	s_waitcnt lgkmcnt(10)
	v_mfma_f32_16x16x32_bf16 v[204:207], v[240:243], v[192:195], v[204:207]
	s_waitcnt lgkmcnt(8)
	v_mfma_f32_16x16x32_bf16 v[208:211], v[144:147], v[192:195], v[208:211]
	v_cvt_pk_bf16_f32 v100, v164, v165
	v_cvt_pk_bf16_f32 v101, v166, v167
	v_and_b32_e32 v188, v100, v96
	v_and_b32_e32 v189, v101, v97
	v_and_b32_e32 v190, v100, v98
	v_and_b32_e32 v191, v101, v99
	s_waitcnt lgkmcnt(7)
	v_add_u32_e32 v219, s79, v88
	v_add_u32_e32 v86, s79, v89
	v_add_u32_e32 v87, s79, v90
	v_add_u32_e32 v92, s79, v91
	ds_read_b64_tr_b16 v[232:233], v219
	ds_read_b64_tr_b16 v[234:235], v219 offset:2048
	ds_read_b64_tr_b16 v[236:237], v86
	ds_read_b64_tr_b16 v[238:239], v86 offset:2048
	ds_read_b64_tr_b16 v[240:241], v87
	ds_read_b64_tr_b16 v[242:243], v87 offset:2048
	ds_read_b64_tr_b16 v[144:145], v92
	ds_read_b64_tr_b16 v[146:147], v92 offset:2048
	s_waitcnt lgkmcnt(14)
	v_mfma_f32_16x16x32_bf16 v[196:199], v[212:215], v[188:191], v[196:199]
	s_waitcnt lgkmcnt(12)
	v_mfma_f32_16x16x32_bf16 v[200:203], v[220:223], v[188:191], v[200:203]
	s_waitcnt lgkmcnt(10)
	v_mfma_f32_16x16x32_bf16 v[204:207], v[224:227], v[188:191], v[204:207]
	s_waitcnt lgkmcnt(8)
	v_mfma_f32_16x16x32_bf16 v[208:211], v[228:231], v[188:191], v[208:211]
	v_cvt_pk_bf16_f32 v100, v168, v169
	v_cvt_pk_bf16_f32 v101, v170, v171
	v_and_b32_e32 v192, v100, v96
	v_and_b32_e32 v193, v101, v97
	v_and_b32_e32 v194, v100, v98
	v_and_b32_e32 v195, v101, v99
	s_waitcnt lgkmcnt(7)
	v_add_u32_e32 v219, s80, v88
	v_add_u32_e32 v86, s80, v89
	v_add_u32_e32 v87, s80, v90
	v_add_u32_e32 v92, s80, v91
	ds_read_b64_tr_b16 v[212:213], v219
	ds_read_b64_tr_b16 v[214:215], v219 offset:2048
	ds_read_b64_tr_b16 v[220:221], v86
	ds_read_b64_tr_b16 v[222:223], v86 offset:2048
	ds_read_b64_tr_b16 v[224:225], v87
	ds_read_b64_tr_b16 v[226:227], v87 offset:2048
	ds_read_b64_tr_b16 v[228:229], v92
	ds_read_b64_tr_b16 v[230:231], v92 offset:2048
	s_waitcnt lgkmcnt(14)
	v_mfma_f32_16x16x32_bf16 v[196:199], v[232:235], v[192:195], v[196:199]
	s_waitcnt lgkmcnt(12)
	v_mfma_f32_16x16x32_bf16 v[200:203], v[236:239], v[192:195], v[200:203]
	s_waitcnt lgkmcnt(10)
	v_mfma_f32_16x16x32_bf16 v[204:207], v[240:243], v[192:195], v[204:207]
	s_waitcnt lgkmcnt(8)
	v_mfma_f32_16x16x32_bf16 v[208:211], v[144:147], v[192:195], v[208:211]
	v_cvt_pk_bf16_f32 v100, v172, v173
	v_cvt_pk_bf16_f32 v101, v174, v175
	v_and_b32_e32 v188, v100, v96
	v_and_b32_e32 v189, v101, v97
	v_and_b32_e32 v190, v100, v98
	v_and_b32_e32 v191, v101, v99
	s_waitcnt lgkmcnt(7)
	v_add_u32_e32 v219, s81, v88
	v_add_u32_e32 v86, s81, v89
	v_add_u32_e32 v87, s81, v90
	v_add_u32_e32 v92, s81, v91
	ds_read_b64_tr_b16 v[232:233], v219
	ds_read_b64_tr_b16 v[234:235], v219 offset:2048
	ds_read_b64_tr_b16 v[236:237], v86
	ds_read_b64_tr_b16 v[238:239], v86 offset:2048
	ds_read_b64_tr_b16 v[240:241], v87
	ds_read_b64_tr_b16 v[242:243], v87 offset:2048
	ds_read_b64_tr_b16 v[144:145], v92
	ds_read_b64_tr_b16 v[146:147], v92 offset:2048
	s_waitcnt lgkmcnt(14)
	v_mfma_f32_16x16x32_bf16 v[196:199], v[212:215], v[188:191], v[196:199]
	s_waitcnt lgkmcnt(12)
	v_mfma_f32_16x16x32_bf16 v[200:203], v[220:223], v[188:191], v[200:203]
	s_waitcnt lgkmcnt(10)
	v_mfma_f32_16x16x32_bf16 v[204:207], v[224:227], v[188:191], v[204:207]
	s_waitcnt lgkmcnt(8)
	v_mfma_f32_16x16x32_bf16 v[208:211], v[228:231], v[188:191], v[208:211]
	v_cvt_pk_bf16_f32 v100, v176, v177
	v_cvt_pk_bf16_f32 v101, v178, v179
	v_and_b32_e32 v192, v100, v96
	v_and_b32_e32 v193, v101, v97
	v_and_b32_e32 v194, v100, v98
	v_and_b32_e32 v195, v101, v99
	s_waitcnt lgkmcnt(7)
	v_add_u32_e32 v219, s82, v88
	v_add_u32_e32 v86, s82, v89
	v_add_u32_e32 v87, s82, v90
	v_add_u32_e32 v92, s82, v91
	ds_read_b64_tr_b16 v[212:213], v219
	ds_read_b64_tr_b16 v[214:215], v219 offset:2048
	ds_read_b64_tr_b16 v[220:221], v86
	ds_read_b64_tr_b16 v[222:223], v86 offset:2048
	ds_read_b64_tr_b16 v[224:225], v87
	ds_read_b64_tr_b16 v[226:227], v87 offset:2048
	ds_read_b64_tr_b16 v[228:229], v92
	ds_read_b64_tr_b16 v[230:231], v92 offset:2048
	s_waitcnt lgkmcnt(14)
	v_mfma_f32_16x16x32_bf16 v[196:199], v[232:235], v[192:195], v[196:199]
	s_waitcnt lgkmcnt(12)
	v_mfma_f32_16x16x32_bf16 v[200:203], v[236:239], v[192:195], v[200:203]
	s_waitcnt lgkmcnt(10)
	v_mfma_f32_16x16x32_bf16 v[204:207], v[240:243], v[192:195], v[204:207]
	s_waitcnt lgkmcnt(8)
	v_mfma_f32_16x16x32_bf16 v[208:211], v[144:147], v[192:195], v[208:211]
	v_cvt_pk_bf16_f32 v100, v180, v181
	v_cvt_pk_bf16_f32 v101, v182, v183
	v_and_b32_e32 v188, v100, v96
	v_and_b32_e32 v189, v101, v97
	v_and_b32_e32 v190, v100, v98
	v_and_b32_e32 v191, v101, v99
	s_waitcnt lgkmcnt(7)
	v_add_u32_e32 v219, s83, v88
	v_add_u32_e32 v86, s83, v89
	v_add_u32_e32 v87, s83, v90
	v_add_u32_e32 v92, s83, v91
	ds_read_b64_tr_b16 v[232:233], v219
	ds_read_b64_tr_b16 v[234:235], v219 offset:2048
	ds_read_b64_tr_b16 v[236:237], v86
	ds_read_b64_tr_b16 v[238:239], v86 offset:2048
	ds_read_b64_tr_b16 v[240:241], v87
	ds_read_b64_tr_b16 v[242:243], v87 offset:2048
	ds_read_b64_tr_b16 v[144:145], v92
	ds_read_b64_tr_b16 v[146:147], v92 offset:2048
	s_waitcnt lgkmcnt(14)
	v_mfma_f32_16x16x32_bf16 v[196:199], v[212:215], v[188:191], v[196:199]
	s_waitcnt lgkmcnt(12)
	v_mfma_f32_16x16x32_bf16 v[200:203], v[220:223], v[188:191], v[200:203]
	s_waitcnt lgkmcnt(10)
	v_mfma_f32_16x16x32_bf16 v[204:207], v[224:227], v[188:191], v[204:207]
	s_waitcnt lgkmcnt(8)
	v_mfma_f32_16x16x32_bf16 v[208:211], v[228:231], v[188:191], v[208:211]
	v_cvt_pk_bf16_f32 v100, v184, v185
	v_cvt_pk_bf16_f32 v101, v186, v187
	v_and_b32_e32 v192, v100, v96
	v_and_b32_e32 v193, v101, v97
	v_and_b32_e32 v194, v100, v98
	v_and_b32_e32 v195, v101, v99
	s_nop 1
	s_waitcnt lgkmcnt(6)
; #define LAS __attribute__((address_space(3)))
; __device__ __forceinline__ size_t tmo(int row, int ct, int nct) { return ((size_t)(row >> 8) * nct + ct) * 32768 + (size_t)(row & 255) * 128; }
; __device__ __forceinline__ void attn_b_commit(LAS unsigned char* lds, const v4u (&kr)[9], const v4u (&vr)[9], const float (&tr)[2]) {
;     const int tid = threadIdx.x; LAS unsigned char* Kl = lds + B_KOFF; LAS unsigned char* Vl = lds + B_VOFF; LAS float* T = (LAS float*)(lds + B_TOFF);
; #pragma unroll
;     for (int k = 0; k < 9; ++k) { const int it = tid + k * NTHREADS; const int row = it >> 3, ch = it & 7;
;         *(LAS v4u*)(Kl + swz(row, ch)) = kr[k]; *(LAS v4u*)(Vl + swz(row, ch)) = vr[k]; }
; #pragma unroll
;     for (int k = 0; k < 2; ++k) { const int it = tid + k * NTHREADS; if (it < B_TSIZE) T[it] = tr[k]; }
; }
; __device__ __forceinline__ void attn_b_unit(LAS unsigned char* lds, const bf16* Z, bf16* Y, int unit) {
;     const int tid = threadIdx.x, lane = tid & 63, wid = tid >> 6, lq = lane & 15, g = lane >> 4;
;     const int rp = unit & 63, h = (unit >> 6) & 7, b = unit >> 9;
;     const size_t tok0 = (size_t)b * SEQ;
;     const int R0 = clampi(2 * rp - 4, 0, 120);
;     LAS unsigned char* Kl = lds + B_KOFF; LAS unsigned char* Vl = lds + B_VOFF; LAS float* T = (LAS float*)(lds + B_TOFF);
;     const int rq = 2 * rp + (wid >> 2), cb = wid & 3, c = 16 * cb + lq;
;     const int r0q = clampi(rq - 4, 0, 120), kc0 = clampi(16 * cb - 8, 0, 32), cs = clampi(c - 8, 0, 48);
;     const size_t qtok = tok0 + (size_t)rq * 64 + c;
;     const unsigned char* qp = (const unsigned char*)Z + tmo((int)qtok, Z_QB / 64 + h, ZLD / 64) + 16 * g;
;     const bf16x8 qf0 = *(const bf16x8*)qp, qf1 = *(const bf16x8*)(qp + 64);
;     ...
;     { const float mm = fmaxf(m0, m1), a0 = __builtin_amdgcn_exp2f(m0 - mm), a1 = __builtin_amdgcn_exp2f(m1 - mm);
;       l0 = l0 * a0 + l1 * a1;
; #pragma unroll
;       for (int d = 0; d < 4; ++d) O0[d] = O0[d] * a0 + O1[d] * a1; }
;     store_o((bf16*)((unsigned char*)Y + tmo((int)qtok, 8 + h, 16)), g, l0, O0);
	v_mfma_f32_16x16x32_bf16 v[196:199], v[232:235], v[192:195], v[196:199]
	s_waitcnt lgkmcnt(4)
	v_mfma_f32_16x16x32_bf16 v[200:203], v[236:239], v[192:195], v[200:203]
	s_waitcnt lgkmcnt(2)
	v_mfma_f32_16x16x32_bf16 v[204:207], v[240:243], v[192:195], v[204:207]
	s_waitcnt lgkmcnt(0)
	v_mfma_f32_16x16x32_bf16 v[208:211], v[144:147], v[192:195], v[208:211]
	v_mov_b32_e32 v100, v245
	s_nop 1
	v_permlane16_swap_b32_e32 v245, v100
	v_add_f32_e32 v245, v245, v100
	v_mov_b32_e32 v100, v245
	s_nop 1
	v_permlane32_swap_b32_e32 v245, v100
	v_add_f32_e32 v245, v245, v100
	v_div_scale_f32 v142, s[50:51], v245, v245, 1.0
	v_div_scale_f32 v216, vcc, 1.0, v245, 1.0
	v_rcp_f32_e32 v143, v142
	s_nop 0
	v_fma_f32 v217, -v142, v143, 1.0
	v_fmac_f32_e32 v143, v217, v143
	v_mul_f32_e32 v148, v216, v143
	v_fma_f32 v149, -v142, v148, v216
	v_fmac_f32_e32 v148, v149, v143
	v_fma_f32 v216, -v142, v148, v216
	v_div_fmas_f32 v216, v216, v143, v148
	v_div_fixup_f32 v216, v216, v245, 1.0
	v_mul_f32_e32 v100, v196, v216
	v_mul_f32_e32 v101, v197, v216
	v_mul_f32_e32 v142, v198, v216
	v_mul_f32_e32 v143, v199, v216
	v_cvt_pk_bf16_f32 v78, v100, v101
	v_cvt_pk_bf16_f32 v79, v142, v143
	v_mul_f32_e32 v100, v200, v216
	v_mul_f32_e32 v101, v201, v216
	v_mul_f32_e32 v142, v202, v216
	v_mul_f32_e32 v143, v203, v216
	v_cvt_pk_bf16_f32 v80, v100, v101
	v_cvt_pk_bf16_f32 v81, v142, v143
	v_mul_f32_e32 v100, v204, v216
	v_mul_f32_e32 v101, v205, v216
	v_mul_f32_e32 v142, v206, v216
	v_mul_f32_e32 v143, v207, v216
	v_cvt_pk_bf16_f32 v82, v100, v101
	v_cvt_pk_bf16_f32 v83, v142, v143
	v_mul_f32_e32 v100, v208, v216
	v_mul_f32_e32 v101, v209, v216
	v_mul_f32_e32 v142, v210, v216
	v_mul_f32_e32 v143, v211, v216
	v_cvt_pk_bf16_f32 v84, v100, v101
	v_cvt_pk_bf16_f32 v85, v142, v143
	s_nop 1
	v_permlane16_swap_b32_e32 v78, v80
	v_permlane16_swap_b32_e32 v79, v81
	v_permlane16_swap_b32_e32 v82, v84
	v_permlane16_swap_b32_e32 v83, v85
	s_nop 0
	v_permlane32_swap_b32_e32 v78, v82
	v_permlane32_swap_b32_e32 v79, v83
	v_permlane32_swap_b32_e32 v80, v84
	v_permlane32_swap_b32_e32 v81, v85
	s_andn2_b64 vcc, exec, s[44:45]
	global_store_dwordx4 v[60:61], v[78:81], off
	global_store_dwordx4 v[60:61], v[82:85], off offset:16
	s_barrier
	s_cbranch_vccz .LBB0_294
.LBB0_281:
	s_cmp_eq_u32 s88, 0
	s_cbranch_scc1 .Lb_small_commit
	s_and_b32 s84, s72, 63
	s_lshl_b32 s84, s84, 1
	s_sub_i32 s84, s84, 4
	s_max_i32 s84, s84, 0
	s_min_i32 s84, s84, 0x78
	v_add_u32_e32 v58, s0, v109
	s_waitcnt vmcnt(13)
	ds_write_b128 v123, v[2:5]
	s_waitcnt vmcnt(12)
	ds_write_b128 v124, v[6:9]
	s_waitcnt vmcnt(11)
	ds_write_b128 v125, v[10:13]
	s_waitcnt vmcnt(10)
	ds_write_b128 v126, v[14:17]
	s_waitcnt vmcnt(9)
	ds_write_b128 v123, v[18:21] offset:16384
	s_waitcnt vmcnt(8)
	ds_write_b128 v127, v[22:25]
	s_waitcnt vmcnt(7)
	ds_write_b128 v128, v[26:29]
	s_waitcnt vmcnt(6)
	ds_write_b128 v129, v[30:33]
	s_waitcnt vmcnt(5)
	ds_write_b128 v123, v[34:37] offset:32768
	s_waitcnt vmcnt(4)
	ds_write_b128 v130, v[38:41]
	s_waitcnt vmcnt(3)
	ds_write_b128 v131, v[42:45]
	s_waitcnt vmcnt(2)
	ds_write_b128 v132, v[46:49]
	s_waitcnt vmcnt(1)
	ds_write_b128 v123, v[50:53] offset:49152
	s_waitcnt vmcnt(0)
	ds_write_b128 v133, v[54:57]
	ds_write_b128 v138, v[66:69]
	ds_write_b128 v139, v[62:65]
	ds_write_b128 v140, v[74:77]
	ds_write_b128 v58, v[70:73]
	v_mul_f32_e32 v141, 0x3fb8aa3b, v141
	s_and_saveexec_b64 s[44:45], s[22:23]
	ds_write_b32 v110, v141
	s_or_b64 exec, exec, s[44:45]
	s_and_saveexec_b64 s[44:45], s[4:5]
	ds_write_b32 v111, v108
	s_or_b64 exec, exec, s[44:45]
	s_xor_b32 s88, s91, 1
	s_branch .Lb_commit_done
.Lb_small_commit:
	s_cmp_eq_u32 s85, 0
	s_cbranch_scc1 .Lb_commit_done
	s_waitcnt vmcnt(0)
	v_add_u32_e32 v58, s86, v123
	v_add_u32_e32 v60, s86, v124
	ds_write_b128 v58, v[2:5]
	ds_write_b128 v60, v[6:9]
	s_cmp_lt_i32 s87, 0
	s_cbranch_scc1 .Lb_commit_done
	v_add_u32_e32 v58, s87, v123
	v_add_u32_e32 v60, s87, v124
	ds_write_b128 v58, v[10:13]
	ds_write_b128 v60, v[14:17]
.Lb_commit_done:
	s_and_b32 s51, s58, 0x7e
	v_add_u32_e32 v86, s51, v115
	s_and_b32 s26, s59, 0xffffe000
	v_lshlrev_b32_e32 v87, 6, v86
	v_add_u32_e32 v88, s26, v87
	s_bfe_u32 s50, s72, 0x30006
	v_ashrrev_i32_e32 v88, 8, v88
	s_add_i32 s26, s50, 12
	v_mul_hi_i32_i24_e32 v91, 0x44, v88
	v_mul_i32_i24_e32 v90, 0x44, v88
	v_or_b32_e32 v87, v87, v116
	v_lshl_add_u64 v[90:91], v[90:91], 0, s[26:27]
	v_lshlrev_b64 v[90:91], 15, v[90:91]
	v_lshlrev_b32_e32 v87, 7, v87
	v_and_b32_e32 v88, 0x7f80, v87
	v_mov_b32_e32 v89, 0
	v_lshl_add_u64 v[90:91], s[38:39], 0, v[90:91]
	v_lshl_add_u64 v[90:91], v[90:91], 0, v[88:89]
	v_lshl_add_u64 v[90:91], v[90:91], 0, v[104:105]
	global_load_dwordx4 v[82:85], v[90:91], off
	global_load_dwordx4 v[78:81], v[90:91], off offset:64
	s_add_i32 s55, s72, s90
	s_and_b32 s50, s55, 15
	s_min_u32 s50, s50, 1
	s_cmpk_lt_i32 s55, 0x1000
	s_cselect_b32 s51, 1, 0
	s_cmp_lg_u32 s91, 0
	s_cselect_b32 s26, s50, s51
	s_cmp_lg_u32 s26, 0
	s_cselect_b64 s[44:45], 0, -1
	s_waitcnt lgkmcnt(0)
	s_barrier
	s_cmp_eq_u32 s26, 0
	s_cbranch_scc1 .Lb_nonext
	s_cmp_lg_u32 s91, 0
	s_cbranch_scc1 .Lb_small_prefetch
; __device__ __forceinline__ size_t tmo(int row, int ct, int nct) { return ((size_t)(row >> 8) * nct + ct) * 32768 + (size_t)(row & 255) * 128; }
; __device__ __forceinline__ void attn_b_prefetch(const bf16* Z, const float* rpb, int unit, v4u (&kr)[9], v4u (&vr)[9], float (&tr)[2]) {
;     const int tid = threadIdx.x; const int rp = unit & 63, h = (unit >> 6) & 7, b = unit >> 9;
;     const size_t tok0 = (size_t)b * SEQ; const int R0 = clampi(2 * rp - 4, 0, 120);
; #pragma unroll
;     for (int k = 0; k < 9; ++k) { const int it = tid + k * NTHREADS; const int row = it >> 3, ch = it & 7, gr = R0 + (row >> 6);
;         kr[k] = (v4u){0u, 0u, 0u, 0u}; vr[k] = (v4u){0u, 0u, 0u, 0u};
;         if (gr < 128) { const int t = (int)tok0 + gr * 64 + (row & 63); kr[k] = *(const v4u*)((const unsigned char*)Z + tmo(t, Z_KB / 64 + h, ZLD / 64) + ch * 16); vr[k] = *(const v4u*)((const unsigned char*)Z + tmo(t, Z_VB / 64 + h, ZLD / 64) + ch * 16); } }
; #pragma unroll
;     for (int k = 0; k < 2; ++k) { const int it = tid + k * NTHREADS, e = it - 16, dr = e >> 5, dc = e & 31;
;         tr[k] = (it >= B_TREAL) ? -INFINITY : ((e >= 0 && dr < 15 && dc < 31) ? rpb[h * 465 + dr * 31 + dc] * LOG2E : 0.f); }
	s_add_i32 s57, s3, s58
	s_and_b32 s26, s57, 0x7e
	v_sub_co_u32_e64 v2, s[50:51], s26, 4
	s_add_i32 s56, s1, s59
	v_readfirstlane_b32 s26, v2
	s_bfe_u32 s73, s55, 0x30006
	s_and_b32 s74, s56, 0xffffe000
	s_min_u32 s26, s26, 0x78
	s_and_b64 s[50:51], s[50:51], exec
	s_cselect_b32 s75, 0, s26
	v_or_b32_e32 v60, s75, v106
	v_lshlrev_b32_e32 v70, 6, v60
	v_or_b32_e32 v2, s74, v70
	v_add_u32_e32 v10, 64, v70
	v_lshrrev_b32_e32 v2, 8, v2
	v_or_b32_e32 v11, s74, v10
	v_add_u32_e32 v18, 0x80, v70
	v_mul_i32_i24_e32 v2, 0x44, v2
	v_or_b32_e32 v14, v10, v107
	v_lshrrev_b32_e32 v10, 8, v11
	v_or_b32_e32 v19, s74, v18
	v_add_u32_e32 v26, 0xc0, v70
	s_add_i32 s26, s73, 20
	s_add_i32 s50, s73, 28
	s_mov_b32 s51, s27
	v_ashrrev_i32_e32 v3, 31, v2
	v_mul_i32_i24_e32 v10, 0x44, v10
	v_or_b32_e32 v22, v18, v107
	v_lshrrev_b32_e32 v18, 8, v19
	v_or_b32_e32 v27, s74, v26
	v_add_u32_e32 v34, 0x100, v70
	v_or_b32_e32 v6, v70, v107
	v_lshl_add_u64 v[4:5], v[2:3], 0, s[26:27]
	v_lshl_add_u64 v[2:3], v[2:3], 0, s[50:51]
	v_ashrrev_i32_e32 v11, 31, v10
	v_mul_i32_i24_e32 v18, 0x44, v18
	v_or_b32_e32 v30, v26, v107
	v_lshrrev_b32_e32 v26, 8, v27
	v_or_b32_e32 v35, s74, v34
	v_add_u32_e32 v42, 0x140, v70
	v_lshlrev_b64 v[4:5], 15, v[4:5]
	v_lshlrev_b32_e32 v6, 7, v6
	v_lshlrev_b64 v[2:3], 15, v[2:3]
	v_lshl_add_u64 v[12:13], v[10:11], 0, s[26:27]
	v_lshl_add_u64 v[10:11], v[10:11], 0, s[50:51]
	v_ashrrev_i32_e32 v19, 31, v18
	v_mul_i32_i24_e32 v26, 0x44, v26
	v_or_b32_e32 v38, v34, v107
	v_lshrrev_b32_e32 v34, 8, v35
	v_or_b32_e32 v43, s74, v42
	v_add_u32_e32 v50, 0x180, v70
	v_and_b32_e32 v58, 0x7f80, v6
	v_lshl_add_u64 v[4:5], s[38:39], 0, v[4:5]
	v_lshl_add_u64 v[2:3], s[38:39], 0, v[2:3]
	v_lshlrev_b64 v[12:13], 15, v[12:13]
	v_lshlrev_b32_e32 v14, 7, v14
	v_lshlrev_b64 v[10:11], 15, v[10:11]
	v_lshl_add_u64 v[20:21], v[18:19], 0, s[26:27]
	v_lshl_add_u64 v[18:19], v[18:19], 0, s[50:51]
	v_ashrrev_i32_e32 v27, 31, v26
	v_mul_i32_i24_e32 v34, 0x44, v34
	v_or_b32_e32 v46, v42, v107
	v_lshrrev_b32_e32 v42, 8, v43
	v_or_b32_e32 v51, s74, v50
	v_lshl_add_u64 v[4:5], v[4:5], 0, v[58:59]
	v_lshl_add_u64 v[2:3], v[2:3], 0, v[58:59]
	v_and_b32_e32 v58, 0x7f80, v14
	v_lshl_add_u64 v[12:13], s[38:39], 0, v[12:13]
	v_lshl_add_u64 v[10:11], s[38:39], 0, v[10:11]
	v_lshlrev_b64 v[20:21], 15, v[20:21]
	v_lshlrev_b32_e32 v22, 7, v22
	v_lshlrev_b64 v[18:19], 15, v[18:19]
	v_lshl_add_u64 v[28:29], v[26:27], 0, s[26:27]
	v_lshl_add_u64 v[26:27], v[26:27], 0, s[50:51]
	v_ashrrev_i32_e32 v35, 31, v34
	v_mul_i32_i24_e32 v42, 0x44, v42
	v_or_b32_e32 v54, v50, v107
	v_lshrrev_b32_e32 v50, 8, v51
	v_lshl_add_u64 v[12:13], v[12:13], 0, v[58:59]
	v_lshl_add_u64 v[10:11], v[10:11], 0, v[58:59]
	v_and_b32_e32 v58, 0x7f80, v22
	v_lshl_add_u64 v[20:21], s[38:39], 0, v[20:21]
	v_lshl_add_u64 v[18:19], s[38:39], 0, v[18:19]
	v_lshlrev_b64 v[28:29], 15, v[28:29]
	v_lshlrev_b32_e32 v30, 7, v30
	v_lshlrev_b64 v[26:27], 15, v[26:27]
	v_lshl_add_u64 v[36:37], v[34:35], 0, s[26:27]
	v_lshl_add_u64 v[34:35], v[34:35], 0, s[50:51]
	v_ashrrev_i32_e32 v43, 31, v42
	v_mul_i32_i24_e32 v50, 0x44, v50
	v_lshl_add_u64 v[20:21], v[20:21], 0, v[58:59]
	v_lshl_add_u64 v[18:19], v[18:19], 0, v[58:59]
	v_and_b32_e32 v58, 0x7f80, v30
	v_lshl_add_u64 v[28:29], s[38:39], 0, v[28:29]
	v_lshl_add_u64 v[26:27], s[38:39], 0, v[26:27]
	v_lshlrev_b64 v[36:37], 15, v[36:37]
	v_lshlrev_b32_e32 v38, 7, v38
	v_lshlrev_b64 v[34:35], 15, v[34:35]
	v_lshl_add_u64 v[44:45], v[42:43], 0, s[26:27]
	v_lshl_add_u64 v[42:43], v[42:43], 0, s[50:51]
	v_ashrrev_i32_e32 v51, 31, v50
	v_lshl_add_u64 v[28:29], v[28:29], 0, v[58:59]
	v_lshl_add_u64 v[26:27], v[26:27], 0, v[58:59]
	v_and_b32_e32 v58, 0x7f80, v38
	v_lshl_add_u64 v[36:37], s[38:39], 0, v[36:37]
	v_lshl_add_u64 v[34:35], s[38:39], 0, v[34:35]
	v_lshlrev_b64 v[44:45], 15, v[44:45]
	v_lshlrev_b32_e32 v46, 7, v46
	v_lshlrev_b64 v[42:43], 15, v[42:43]
	v_lshl_add_u64 v[52:53], v[50:51], 0, s[26:27]
	v_lshl_add_u64 v[50:51], v[50:51], 0, s[50:51]
	v_lshl_add_u64 v[36:37], v[36:37], 0, v[58:59]
	v_lshl_add_u64 v[34:35], v[34:35], 0, v[58:59]
	v_and_b32_e32 v58, 0x7f80, v46
	v_lshl_add_u64 v[44:45], s[38:39], 0, v[44:45]
	v_lshl_add_u64 v[42:43], s[38:39], 0, v[42:43]
	v_lshlrev_b64 v[52:53], 15, v[52:53]
	v_lshlrev_b32_e32 v54, 7, v54
	v_lshlrev_b64 v[50:51], 15, v[50:51]
	v_lshl_add_u64 v[44:45], v[44:45], 0, v[58:59]
	v_lshl_add_u64 v[42:43], v[42:43], 0, v[58:59]
	v_and_b32_e32 v58, 0x7f80, v54
	v_lshl_add_u64 v[52:53], s[38:39], 0, v[52:53]
	v_lshl_add_u64 v[50:51], s[38:39], 0, v[50:51]
	v_lshl_add_u64 v[52:53], v[52:53], 0, v[58:59]
	v_lshl_add_u64 v[50:51], v[50:51], 0, v[58:59]
	v_lshl_add_u64 v[4:5], v[4:5], 0, v[102:103]
	v_lshl_add_u64 v[6:7], v[2:3], 0, v[102:103]
	v_lshl_add_u64 v[12:13], v[12:13], 0, v[102:103]
	v_lshl_add_u64 v[14:15], v[10:11], 0, v[102:103]
	v_lshl_add_u64 v[20:21], v[20:21], 0, v[102:103]
	v_lshl_add_u64 v[22:23], v[18:19], 0, v[102:103]
	v_lshl_add_u64 v[28:29], v[28:29], 0, v[102:103]
	v_lshl_add_u64 v[30:31], v[26:27], 0, v[102:103]
	v_lshl_add_u64 v[36:37], v[36:37], 0, v[102:103]
	v_lshl_add_u64 v[38:39], v[34:35], 0, v[102:103]
	v_lshl_add_u64 v[44:45], v[44:45], 0, v[102:103]
	v_lshl_add_u64 v[46:47], v[42:43], 0, v[102:103]
	v_lshl_add_u64 v[52:53], v[52:53], 0, v[102:103]
	v_lshl_add_u64 v[54:55], v[50:51], 0, v[102:103]
	global_load_dwordx4 v[2:5], v[4:5], off
	s_nop 0
	global_load_dwordx4 v[6:9], v[6:7], off
	s_nop 0
	global_load_dwordx4 v[10:13], v[12:13], off
	s_nop 0
	global_load_dwordx4 v[14:17], v[14:15], off
	s_nop 0
	global_load_dwordx4 v[18:21], v[20:21], off
	s_nop 0
	global_load_dwordx4 v[22:25], v[22:23], off
	s_nop 0
	global_load_dwordx4 v[26:29], v[28:29], off
	s_nop 0
	global_load_dwordx4 v[30:33], v[30:31], off
	s_nop 0
	global_load_dwordx4 v[34:37], v[36:37], off
	s_nop 0
	global_load_dwordx4 v[38:41], v[38:39], off
	s_nop 0
	global_load_dwordx4 v[42:45], v[44:45], off
	s_nop 0
	global_load_dwordx4 v[46:49], v[46:47], off
	s_nop 0
	global_load_dwordx4 v[50:53], v[52:53], off
	s_nop 0
	global_load_dwordx4 v[54:57], v[54:55], off
	v_cmp_gt_u32_e32 vcc, s52, v60
	v_mov_b32_e32 v60, v59
	v_mov_b32_e32 v61, v59
	v_mov_b32_e32 v58, v59
	v_mov_b64_e32 v[64:65], v[60:61]
	v_mov_b64_e32 v[68:69], v[60:61]
	v_mov_b64_e32 v[62:63], v[58:59]
	v_mov_b64_e32 v[66:67], v[58:59]
	s_and_saveexec_b64 s[70:71], vcc
	s_cbranch_execz .LBB0_290
; __device__ __forceinline__ size_t tmo(int row, int ct, int nct) { return ((size_t)(row >> 8) * nct + ct) * 32768 + (size_t)(row & 255) * 128; }
; __device__ __forceinline__ void attn_b_prefetch(const bf16* Z, const float* rpb, int unit, v4u (&kr)[9], v4u (&vr)[9], float (&tr)[2]) {
;     ...
;     for (int k = 0; k < 9; ++k) { const int it = tid + k * NTHREADS; const int row = it >> 3, ch = it & 7, gr = R0 + (row >> 6);
;         kr[k] = (v4u){0u, 0u, 0u, 0u}; vr[k] = (v4u){0u, 0u, 0u, 0u};
;         if (gr < 128) { const int t = (int)tok0 + gr * 64 + (row & 63); kr[k] = *(const v4u*)((const unsigned char*)Z + tmo(t, Z_KB / 64 + h, ZLD / 64) + ch * 16); vr[k] = *(const v4u*)((const unsigned char*)Z + tmo(t, Z_VB / 64 + h, ZLD / 64) + ch * 16); } }
	v_add_u32_e32 v58, 0x1c0, v70
	v_or_b32_e32 v60, s74, v58
	v_lshrrev_b32_e32 v60, 8, v60
	v_mul_i32_i24_e32 v60, 0x44, v60
	v_ashrrev_i32_e32 v61, 31, v60
	v_or_b32_e32 v58, v58, v107
	v_lshl_add_u64 v[62:63], v[60:61], 0, s[26:27]
	v_lshlrev_b64 v[62:63], 15, v[62:63]
	v_lshlrev_b32_e32 v58, 7, v58
	v_lshl_add_u64 v[60:61], v[60:61], 0, s[50:51]
	v_and_b32_e32 v58, 0x7f80, v58
	v_lshl_add_u64 v[62:63], s[38:39], 0, v[62:63]
	v_lshlrev_b64 v[60:61], 15, v[60:61]
	v_lshl_add_u64 v[62:63], v[62:63], 0, v[58:59]
	v_lshl_add_u64 v[60:61], s[38:39], 0, v[60:61]
	v_lshl_add_u64 v[62:63], v[62:63], 0, v[102:103]
	v_lshl_add_u64 v[60:61], v[60:61], 0, v[58:59]
	v_lshl_add_u64 v[60:61], v[60:61], 0, v[102:103]
	global_load_dwordx4 v[66:69], v[62:63], off
	s_nop 0
	global_load_dwordx4 v[62:65], v[60:61], off

; __device__ __forceinline__ size_t tmo(int row, int ct, int nct) { return ((size_t)(row >> 8) * nct + ct) * 32768 + (size_t)(row & 255) * 128; }
; __device__ __forceinline__ void attn_b_prefetch(const bf16* Z, const float* rpb, int unit, v4u (&kr)[9], v4u (&vr)[9], float (&tr)[2]) {
;     const int tid = threadIdx.x; const int rp = unit & 63, h = (unit >> 6) & 7, b = unit >> 9;
;     const size_t tok0 = (size_t)b * SEQ; const int R0 = clampi(2 * rp - 4, 0, 120);
; #pragma unroll
;     for (int k = 0; k < 9; ++k) { const int it = tid + k * NTHREADS; const int row = it >> 3, ch = it & 7, gr = R0 + (row >> 6);
;         kr[k] = (v4u){0u, 0u, 0u, 0u}; vr[k] = (v4u){0u, 0u, 0u, 0u};
;         if (gr < 128) { const int t = (int)tok0 + gr * 64 + (row & 63); kr[k] = *(const v4u*)((const unsigned char*)Z + tmo(t, Z_KB / 64 + h, ZLD / 64) + ch * 16); vr[k] = *(const v4u*)((const unsigned char*)Z + tmo(t, Z_VB / 64 + h, ZLD / 64) + ch * 16); } }
.Lb_small_prefetch:
	s_and_b32 s26, s72, 63
	s_lshl_b32 s26, s26, 1
	s_sub_i32 s26, s26, 4
	s_max_i32 s26, s26, 0
	s_min_i32 s26, s26, 0x78
	s_and_b32 s73, s55, 63
	s_lshl_b32 s73, s73, 1
	s_sub_i32 s73, s73, 4
	s_max_i32 s73, s73, 0
	s_min_i32 s73, s73, 0x78
	s_mov_b32 s85, 0
	s_cmp_eq_u32 s26, s73
	s_cbranch_scc1 .Lb_nonext
	s_mov_b32 s85, 1
	s_add_i32 s74, s73, 7
	s_add_i32 s75, s73, 8
	s_sub_i32 s86, s74, s84
	s_mul_i32 s26, s86, 57
	s_lshr_b32 s26, s26, 9
	s_mul_i32 s26, s26, 9
	s_sub_i32 s86, s86, s26
	s_lshl_b32 s86, s86, 13
	s_sub_i32 s87, s75, s84
	s_mul_i32 s26, s87, 57
	s_lshr_b32 s26, s26, 9
	s_mul_i32 s26, s26, 9
	s_sub_i32 s87, s87, s26
	s_lshl_b32 s87, s87, 13
	s_cmpk_lt_i32 s75, 0x80
	s_cselect_b32 s87, s87, -1
	s_min_i32 s75, s75, 0x7f
	s_lshr_b32 s26, s55, 9
	s_lshl_b32 s26, s26, 5
	s_bfe_u32 s73, s55, 0x30006
	s_lshr_b32 s50, s74, 2
	s_add_i32 s50, s50, s26
	s_mul_i32 s50, s50, 0x44
	s_add_i32 s50, s50, s73
	s_add_i32 s76, s50, 20
	s_mov_b32 s77, 0
	s_lshl_b64 s[76:77], s[76:77], 15
	s_add_i32 s78, s50, 28
	s_mov_b32 s79, 0
	s_lshl_b64 s[78:79], s[78:79], 15
	s_and_b32 s50, s74, 3
	s_lshl_b32 s50, s50, 13
	s_add_u32 s76, s76, s50
	s_addc_u32 s77, s77, 0
	s_add_u32 s78, s78, s50
	s_addc_u32 s79, s79, 0
	s_add_u32 s76, s76, s38
	s_addc_u32 s77, s77, s39
	s_add_u32 s78, s78, s38
	s_addc_u32 s79, s79, s39
	s_lshr_b32 s50, s75, 2
	s_add_i32 s50, s50, s26
	s_mul_i32 s50, s50, 0x44
	s_add_i32 s50, s50, s73
	s_add_i32 s80, s50, 20
	s_mov_b32 s81, 0
	s_lshl_b64 s[80:81], s[80:81], 15
	s_add_i32 s82, s50, 28
	s_mov_b32 s83, 0
	s_lshl_b64 s[82:83], s[82:83], 15
	s_and_b32 s50, s75, 3
	s_lshl_b32 s50, s50, 13
	s_add_u32 s80, s80, s50
	s_addc_u32 s81, s81, 0
	s_add_u32 s82, s82, s50
	s_addc_u32 s83, s83, 0
	s_add_u32 s80, s80, s38
	s_addc_u32 s81, s81, s39
	s_add_u32 s82, s82, s38
	s_addc_u32 s83, s83, s39
	v_lshl_or_b32 v18, v107, 7, v102
	global_load_dwordx4 v[2:5], v18, s[76:77]
	global_load_dwordx4 v[6:9], v18, s[78:79]
	global_load_dwordx4 v[10:13], v18, s[80:81]
	global_load_dwordx4 v[14:17], v18, s[82:83]
	s_branch .LBB0_280
